# v22
# speedup vs baseline: 1.0158x; 1.0158x over previous
.LBB0_69:
	s_add_i32 s4, s4, 1
	s_cmp_lg_u32 s4, 16
	s_cselect_b32 s4, s4, 0
	s_add_i32 s6, s5, 0x8000
	s_and_b32 s5, s5, 0x8000
	s_lshl_b32 s8, s4, 6
	s_and_b32 s7, s6, 0x8000
	v_lshl_or_b32 v95, v93, 1, s5
	v_or_b32_e32 v94, s8, v90
	v_add_u32_e32 v96, s7, v89
	s_ashr_i32 s9, s8, 31
	v_add_u32_e32 v118, v95, v64
	v_add_u32_e32 v114, v95, v92
	v_ashrrev_i32_e32 v95, 31, v94
	v_readfirstlane_b32 s7, v96
	v_add_u32_e32 v97, 0x400, v96
	v_add_u32_e32 v98, 0x800, v96
	v_add_u32_e32 v99, 0xc00, v96
	v_add_u32_e32 v100, 0x4000, v96
	s_lshl_b64 s[8:9], s[8:9], 1
	v_add_u32_e32 v101, 0x4400, v96
	v_add_u32_e32 v102, 0x4800, v96
	v_add_u32_e32 v104, 0x4c00, v96
	v_lshlrev_b64 v[94:95], 1, v[94:95]
	v_readfirstlane_b32 s36, v97
	v_readfirstlane_b32 s37, v98
	v_readfirstlane_b32 s72, v99
	v_lshl_add_u64 v[96:97], v[74:75], 0, s[8:9]
	v_readfirstlane_b32 s73, v100
	v_lshl_add_u64 v[98:99], v[76:77], 0, s[8:9]
	v_readfirstlane_b32 s85, v101
	v_lshl_add_u64 v[100:101], v[78:79], 0, s[8:9]
	v_readfirstlane_b32 s86, v102
	v_lshl_add_u64 v[102:103], v[80:81], 0, s[8:9]
	v_readfirstlane_b32 s8, v104
	v_lshl_add_u64 v[104:105], v[66:67], 0, v[94:95]
	s_mov_b32 m0, s7
	s_waitcnt vmcnt(0) lgkmcnt(0)
	s_barrier
	v_lshl_add_u64 v[106:107], v[68:69], 0, v[94:95]
	global_load_lds_dwordx4 v[104:105], off
	s_mov_b32 m0, s36
	v_lshl_add_u64 v[108:109], v[70:71], 0, v[94:95]
	global_load_lds_dwordx4 v[106:107], off
	s_mov_b32 m0, s37
	v_lshl_add_u64 v[94:95], v[72:73], 0, v[94:95]
	global_load_lds_dwordx4 v[108:109], off
	s_mov_b32 m0, s72
	s_cmp_eq_u32 s6, 0x78000
	global_load_lds_dwordx4 v[94:95], off
	s_mov_b32 m0, s73
	s_nop 0
	global_load_lds_dwordx4 v[96:97], off
	s_mov_b32 m0, s85
	s_nop 0
	global_load_lds_dwordx4 v[98:99], off
	s_mov_b32 m0, s86
	s_nop 0
	global_load_lds_dwordx4 v[100:101], off
	s_mov_b32 m0, s8
	s_nop 0
	global_load_lds_dwordx4 v[102:103], off
	ds_read_b128 v[94:97], v114 offset:16384
	ds_read_b128 v[98:101], v114 offset:18432
	ds_read_b128 v[102:105], v118
	ds_read_b128 v[106:109], v118 offset:2048
	ds_read_b128 v[110:113], v114 offset:20480
	ds_read_b128 v[114:117], v114 offset:22528
	s_waitcnt lgkmcnt(0)
	v_mfma_f32_16x16x32_bf16 v[60:63], v[94:97], v[102:105], v[60:63]
	v_mfma_f32_16x16x32_bf16 v[56:59], v[98:101], v[102:105], v[56:59]
	v_mfma_f32_16x16x32_bf16 v[52:55], v[110:113], v[102:105], v[52:55]
	v_mfma_f32_16x16x32_bf16 v[40:43], v[114:117], v[102:105], v[40:43]
	v_mfma_f32_16x16x32_bf16 v[32:35], v[94:97], v[106:109], v[32:35]
	v_mfma_f32_16x16x32_bf16 v[28:31], v[98:101], v[106:109], v[28:31]
	v_mfma_f32_16x16x32_bf16 v[24:27], v[110:113], v[106:109], v[24:27]
	v_mfma_f32_16x16x32_bf16 v[20:23], v[114:117], v[106:109], v[20:23]
	ds_read_b128 v[102:105], v118 offset:4096
	ds_read_b128 v[106:109], v118 offset:6144
	s_waitcnt lgkmcnt(1)
	v_mfma_f32_16x16x32_bf16 v[12:15], v[94:97], v[102:105], v[12:15]
	s_waitcnt lgkmcnt(0)
	v_mfma_f32_16x16x32_bf16 v[44:47], v[94:97], v[106:109], v[44:47]
	v_lshl_or_b32 v94, v91, 1, s5
	v_add_u32_e32 v118, v94, v64
	v_add_u32_e32 v119, v94, v92
	v_mfma_f32_16x16x32_bf16 v[8:11], v[98:101], v[102:105], v[8:11]
	s_mov_b32 s5, s6
	v_mfma_f32_16x16x32_bf16 v[4:7], v[110:113], v[102:105], v[4:7]
	v_mfma_f32_16x16x32_bf16 v[0:3], v[114:117], v[102:105], v[0:3]
	v_mfma_f32_16x16x32_bf16 v[48:51], v[98:101], v[106:109], v[48:51]
	ds_read_b128 v[94:97], v119 offset:16384
	ds_read_b128 v[98:101], v119 offset:18432
	v_mfma_f32_16x16x32_bf16 v[36:39], v[110:113], v[106:109], v[36:39]
	v_mfma_f32_16x16x32_bf16 v[16:19], v[114:117], v[106:109], v[16:19]
	ds_read_b128 v[102:105], v118
	ds_read_b128 v[106:109], v118 offset:2048
	ds_read_b128 v[110:113], v119 offset:20480
	ds_read_b128 v[114:117], v119 offset:22528
	s_waitcnt lgkmcnt(3)
	v_mfma_f32_16x16x32_bf16 v[60:63], v[94:97], v[102:105], v[60:63]
	v_mfma_f32_16x16x32_bf16 v[56:59], v[98:101], v[102:105], v[56:59]
	s_waitcnt lgkmcnt(1)
	v_mfma_f32_16x16x32_bf16 v[52:55], v[110:113], v[102:105], v[52:55]
	s_waitcnt lgkmcnt(0)
	v_mfma_f32_16x16x32_bf16 v[40:43], v[114:117], v[102:105], v[40:43]
	v_mfma_f32_16x16x32_bf16 v[32:35], v[94:97], v[106:109], v[32:35]
	v_mfma_f32_16x16x32_bf16 v[28:31], v[98:101], v[106:109], v[28:31]
	v_mfma_f32_16x16x32_bf16 v[24:27], v[110:113], v[106:109], v[24:27]
	v_mfma_f32_16x16x32_bf16 v[20:23], v[114:117], v[106:109], v[20:23]
	ds_read_b128 v[102:105], v118 offset:4096
	ds_read_b128 v[106:109], v118 offset:6144
	s_waitcnt lgkmcnt(1)
	v_mfma_f32_16x16x32_bf16 v[12:15], v[94:97], v[102:105], v[12:15]
	v_mfma_f32_16x16x32_bf16 v[8:11], v[98:101], v[102:105], v[8:11]
	v_mfma_f32_16x16x32_bf16 v[4:7], v[110:113], v[102:105], v[4:7]
	v_mfma_f32_16x16x32_bf16 v[0:3], v[114:117], v[102:105], v[0:3]
	s_waitcnt lgkmcnt(0)
	v_mfma_f32_16x16x32_bf16 v[44:47], v[94:97], v[106:109], v[44:47]
	v_mfma_f32_16x16x32_bf16 v[48:51], v[98:101], v[106:109], v[48:51]
	v_mfma_f32_16x16x32_bf16 v[36:39], v[110:113], v[106:109], v[36:39]
	v_mfma_f32_16x16x32_bf16 v[16:19], v[114:117], v[106:109], v[16:19]
	s_cbranch_scc0 .LBB0_69
	v_lshlrev_b32_e32 v70, 1, v93
	v_add_u32_e32 v89, v70, v92
	s_waitcnt vmcnt(0)
	s_barrier
	ds_read_b128 v[66:69], v89 offset:49152
	ds_read_b128 v[74:77], v89 offset:51200
	ds_read_b128 v[78:81], v89 offset:53248
	ds_read_b128 v[94:97], v89 offset:55296
	v_add_u32_e32 v90, v70, v64
	ds_read_b128 v[70:73], v90 offset:32768
	s_waitcnt lgkmcnt(0)
	v_mfma_f32_16x16x32_bf16 v[60:63], v[66:69], v[70:73], v[60:63]
	v_lshlrev_b32_e32 v89, 1, v91
	v_add_u32_e32 v106, v89, v92
	v_add_u32_e32 v64, v89, v64
	v_mfma_f32_16x16x32_bf16 v[56:59], v[74:77], v[70:73], v[56:59]
	s_cmp_lt_i32 s34, 5
	s_mov_b32 s72, 0
	v_mfma_f32_16x16x32_bf16 v[52:55], v[78:81], v[70:73], v[52:55]
	v_mfma_f32_16x16x32_bf16 v[40:43], v[94:97], v[70:73], v[40:43]
	ds_read_b128 v[70:73], v90 offset:34816
	s_waitcnt lgkmcnt(0)
	v_mfma_f32_16x16x32_bf16 v[32:35], v[66:69], v[70:73], v[32:35]
	v_mfma_f32_16x16x32_bf16 v[28:31], v[74:77], v[70:73], v[28:31]
	v_mfma_f32_16x16x32_bf16 v[24:27], v[78:81], v[70:73], v[24:27]
	v_mfma_f32_16x16x32_bf16 v[20:23], v[94:97], v[70:73], v[20:23]
	ds_read_b128 v[70:73], v90 offset:36864
	s_waitcnt lgkmcnt(0)
	v_mfma_f32_16x16x32_bf16 v[12:15], v[66:69], v[70:73], v[12:15]
	v_mfma_f32_16x16x32_bf16 v[8:11], v[74:77], v[70:73], v[8:11]
	v_mfma_f32_16x16x32_bf16 v[4:7], v[78:81], v[70:73], v[4:7]
	v_mfma_f32_16x16x32_bf16 v[0:3], v[94:97], v[70:73], v[0:3]
	ds_read_b128 v[70:73], v90 offset:38912
	s_waitcnt lgkmcnt(0)
	v_mfma_f32_16x16x32_bf16 v[44:47], v[66:69], v[70:73], v[44:47]
	ds_read_b128 v[66:69], v106 offset:55296
	ds_read_b128 v[90:93], v106 offset:53248
	v_mfma_f32_16x16x32_bf16 v[48:51], v[74:77], v[70:73], v[48:51]
	ds_read_b128 v[74:77], v64 offset:38912
	ds_read_b128 v[98:101], v64 offset:36864
	ds_read_b128 v[102:105], v106 offset:51200
	ds_read_b128 v[106:109], v106 offset:49152
	v_mfma_f32_16x16x32_bf16 v[36:39], v[78:81], v[70:73], v[36:39]
	ds_read_b128 v[78:81], v64 offset:34816
	ds_read_b128 v[110:113], v64 offset:32768
	v_lshlrev_b32_e32 v64, 6, v88
	s_waitcnt lgkmcnt(0)
	v_mfma_f32_16x16x32_bf16 v[16:19], v[94:97], v[70:73], v[16:19]
	v_add_u32_e32 v70, s71, v64
	v_or_b32_e32 v70, v70, v86
	v_ashrrev_i32_e32 v71, 31, v70
	v_lshl_add_u64 v[70:71], v[70:71], 2, s[24:25]
	s_barrier
	global_load_dword v72, v[70:71], off
	global_load_dword v73, v[70:71], off offset:64
	global_load_dword v88, v[70:71], off offset:128
	s_nop 0
	global_load_dword v70, v[70:71], off offset:192
	v_and_b32_e32 v71, 48, v85
	v_or_b32_e32 v89, v64, v86
	v_lshl_or_b32 v64, v87, 8, v71
	v_mfma_f32_16x16x32_bf16 v[40:43], v[66:69], v[110:113], v[40:43]
	s_barrier
	v_mfma_f32_16x16x32_bf16 v[32:35], v[106:109], v[78:81], v[32:35]
	s_waitcnt vmcnt(3)
	v_fmamk_f32 v71, v72, 0x3a800000, v83
	s_waitcnt vmcnt(2)
	v_fmamk_f32 v72, v73, 0x3a800000, v83
	v_mul_f32_e32 v87, 0x4b800000, v71
	v_cmp_gt_f32_e32 vcc, s38, v71
	s_waitcnt vmcnt(1)
	v_fmamk_f32 v73, v88, 0x3a800000, v83
	v_mul_f32_e32 v88, 0x4b800000, v72
	v_cndmask_b32_e32 v71, v71, v87, vcc
	v_cmp_gt_f32_e64 s[4:5], s38, v72
	v_rsq_f32_e32 v71, v71
	s_waitcnt vmcnt(0)
	v_fmamk_f32 v70, v70, 0x3a800000, v83
	v_cndmask_b32_e64 v72, v72, v88, s[4:5]
	v_mul_f32_e32 v94, 0x4b800000, v73
	v_cmp_gt_f32_e64 s[6:7], s38, v73
	v_rsq_f32_e32 v72, v72
	v_mul_f32_e32 v95, 0x4b800000, v70
	v_cndmask_b32_e64 v73, v73, v94, s[6:7]
	v_cmp_gt_f32_e64 s[8:9], s38, v70
	v_rsq_f32_e32 v73, v73
	v_mfma_f32_16x16x32_bf16 v[28:31], v[102:105], v[78:81], v[28:31]
	v_cndmask_b32_e64 v70, v70, v95, s[8:9]
	v_rsq_f32_e32 v87, v70
	v_mul_f32_e32 v70, 0x45800000, v71
	v_mul_f32_e32 v88, 0x45800000, v72
	v_cndmask_b32_e32 v70, v71, v70, vcc
	v_mfma_f32_16x16x32_bf16 v[24:27], v[90:93], v[78:81], v[24:27]
	v_cndmask_b32_e64 v72, v72, v88, s[4:5]
	v_pk_mul_f32 v[42:43], v[42:43], v[70:71] op_sel_hi:[1,0]
	v_pk_mul_f32 v[40:41], v[40:41], v[70:71] op_sel_hi:[1,0]
	v_mfma_f32_16x16x32_bf16 v[20:23], v[66:69], v[78:81], v[20:23]
	v_mad_u64_u32 v[78:79], s[4:5], v89, s39, v[64:65]
	ds_write_b128 v78, v[40:43] offset:192
	v_mfma_f32_16x16x32_bf16 v[0:3], v[66:69], v[98:101], v[0:3]
	v_mul_f32_e64 v34, v34, v72
	v_mul_f32_e64 v35, v35, v72
	v_pk_mul_f32 v[32:33], v[32:33], v[72:73] op_sel_hi:[1,0]
	v_mul_f32_e32 v94, 0x45800000, v73
	v_mfma_f32_16x16x32_bf16 v[40:43], v[106:109], v[74:77], v[44:47]
	ds_write_b128 v78, v[32:35] offset:8448
	v_pk_mul_f32 v[30:31], v[30:31], v[72:73] op_sel_hi:[1,0]
	v_pk_mul_f32 v[28:29], v[28:29], v[72:73] op_sel_hi:[1,0]
	v_mfma_f32_16x16x32_bf16 v[32:35], v[102:105], v[74:77], v[48:51]
	v_mul_f32_e32 v95, 0x45800000, v87
	v_cndmask_b32_e64 v88, v73, v94, s[6:7]
	ds_write_b128 v78, v[28:31] offset:8512
	v_mfma_f32_16x16x32_bf16 v[28:31], v[90:93], v[74:77], v[36:39]
	v_cndmask_b32_e64 v94, v87, v95, s[8:9]
	v_pk_mul_f32 v[2:3], v[2:3], v[88:89] op_sel_hi:[1,0]
	v_pk_mul_f32 v[0:1], v[0:1], v[88:89] op_sel_hi:[1,0]
	v_mfma_f32_16x16x32_bf16 v[16:19], v[66:69], v[74:77], v[16:19]
	ds_write_b128 v78, v[0:3] offset:17088
	v_pk_mul_f32 v[2:3], v[42:43], v[94:95] op_sel_hi:[1,0]
	v_pk_mul_f32 v[0:1], v[40:41], v[94:95] op_sel_hi:[1,0]
	v_mfma_f32_16x16x32_bf16 v[8:11], v[102:105], v[98:101], v[8:11]
	ds_write_b128 v78, v[0:3] offset:25344
	v_pk_mul_f32 v[2:3], v[34:35], v[94:95] op_sel_hi:[1,0]
	v_pk_mul_f32 v[0:1], v[32:33], v[94:95] op_sel_hi:[1,0]
	v_mfma_f32_16x16x32_bf16 v[60:63], v[106:109], v[110:113], v[60:63]
	ds_write_b128 v78, v[0:3] offset:25408
	v_pk_mul_f32 v[2:3], v[30:31], v[94:95] op_sel_hi:[1,0]
	v_pk_mul_f32 v[0:1], v[28:29], v[94:95] op_sel_hi:[1,0]
	v_mfma_f32_16x16x32_bf16 v[56:59], v[102:105], v[110:113], v[56:59]
	ds_write_b128 v78, v[0:3] offset:25472
	v_pk_mul_f32 v[2:3], v[18:19], v[94:95] op_sel_hi:[1,0]
	v_pk_mul_f32 v[0:1], v[16:17], v[94:95] op_sel_hi:[1,0]
	v_mfma_f32_16x16x32_bf16 v[52:55], v[90:93], v[110:113], v[52:55]
	s_cselect_b64 s[8:9], -1, 0
	s_cmp_gt_i32 s34, 2
	ds_write_b128 v78, v[0:3] offset:25536
	v_mfma_f32_16x16x32_bf16 v[12:15], v[106:109], v[98:101], v[12:15]
	v_lshl_or_b32 v0, v86, 3, s35
	s_cselect_b32 s34, s51, 0x60000
	v_pk_mul_f32 v[10:11], v[10:11], v[88:89] op_sel_hi:[1,0]
	v_mfma_f32_16x16x32_bf16 v[4:7], v[90:93], v[98:101], v[4:7]
	v_mul_f32_e64 v8, v8, v88
	v_mul_f32_e64 v9, v9, v88
	v_ashrrev_i32_e32 v1, 31, v0
	s_add_u32 s34, s24, s34
	v_pk_mul_f32 v[62:63], v[62:63], v[70:71] op_sel_hi:[1,0]
	v_pk_mul_f32 v[60:61], v[60:61], v[70:71] op_sel_hi:[1,0]
	v_pk_mul_f32 v[58:59], v[58:59], v[70:71] op_sel_hi:[1,0]
	v_pk_mul_f32 v[56:57], v[56:57], v[70:71] op_sel_hi:[1,0]
	v_pk_mul_f32 v[54:55], v[54:55], v[70:71] op_sel_hi:[1,0]
	v_pk_mul_f32 v[52:53], v[52:53], v[70:71] op_sel_hi:[1,0]
	v_pk_mul_f32 v[26:27], v[26:27], v[72:73] op_sel_hi:[1,0]
	v_pk_mul_f32 v[24:25], v[24:25], v[72:73] op_sel_hi:[1,0]
	v_pk_mul_f32 v[22:23], v[22:23], v[72:73] op_sel_hi:[1,0]
	v_pk_mul_f32 v[20:21], v[20:21], v[72:73] op_sel_hi:[1,0]
	v_pk_mul_f32 v[14:15], v[14:15], v[88:89] op_sel_hi:[1,0]
	v_pk_mul_f32 v[12:13], v[12:13], v[88:89] op_sel_hi:[1,0]
	ds_write_b128 v78, v[8:11] offset:16960
	v_pk_mul_f32 v[6:7], v[6:7], v[88:89] op_sel_hi:[1,0]
	v_pk_mul_f32 v[4:5], v[4:5], v[88:89] op_sel_hi:[1,0]
	v_lshlrev_b32_e32 v8, 5, v86
	v_cmp_gt_i32_e64 s[4:5], s50, v0
	v_cmp_eq_u32_e64 s[6:7], 0, v86
	v_lshl_add_u64 v[10:11], v[0:1], 1, s[80:81]
	s_addc_u32 s35, s25, 0
	ds_write_b128 v78, v[60:63]
	ds_write_b128 v78, v[56:59] offset:64
	ds_write_b128 v78, v[52:55] offset:128
	ds_write_b128 v78, v[24:27] offset:8576
	ds_write_b128 v78, v[20:23] offset:8640
	ds_write_b128 v78, v[12:15] offset:16896
	ds_write_b128 v78, v[4:7] offset:17024
	s_waitcnt lgkmcnt(0)
	s_barrier
	s_branch .LBB0_73

.LBB0_90:
	s_ashr_i32 s4, s39, 31
	s_lshr_b32 s4, s4, 29
	s_add_i32 s50, s39, s4
	s_and_b32 s4, s50, -8
	s_or_b32 s5, s4, s33
	s_sub_i32 s51, s39, s4
	s_lshl_b32 s4, s5, 7
	s_mul_i32 s5, s5, 5
	s_mul_i32 s57, s51, 3
	s_add_i32 s5, s5, s57
	s_mul_hi_i32 s57, s5, 0x2aaaaaab
	s_lshr_b32 s65, s57, 31
	v_mov_b32_e32 v17, v138
	s_add_i32 s57, s57, s65
	s_mul_i32 s57, s57, 6
	v_bfe_u32 v1, v17, 3, 3
	v_ashrrev_i32_e32 v0, 6, v17
	v_bitop3_b32 v12, v1, v17, 7 bitop3:0x78
	s_sub_i32 s5, s5, s57
	s_lshl_b32 s72, s5, 6
	v_lshl_or_b32 v10, v0, 5, v1
	v_lshlrev_b32_e32 v16, 3, v12
	v_lshlrev_b32_e32 v23, 12, v0
	v_add_u32_e32 v0, s4, v10
	v_or_b32_e32 v2, s72, v16
	v_mad_i64_i32 v[0:1], s[86:87], v0, s15, v[24:25]
	v_ashrrev_i32_e32 v3, 31, v2
	v_lshlrev_b64 v[8:9], 1, v[2:3]
	v_readfirstlane_b32 s86, v23
	v_lshl_add_u64 v[2:3], v[0:1], 0, v[8:9]
	s_mov_b32 m0, s86
	v_or_b32_e32 v13, 8, v10
	global_load_lds_dwordx4 v[2:3], off
	v_add_u32_e32 v2, s4, v13
	v_or_b32_e32 v6, 0x400, v23
	v_mad_i64_i32 v[2:3], s[88:89], v2, s15, v[24:25]
	v_readfirstlane_b32 s87, v6
	v_lshl_add_u64 v[4:5], v[2:3], 0, v[8:9]
	s_mov_b32 m0, s87
	v_or_b32_e32 v14, 16, v10
	global_load_lds_dwordx4 v[4:5], off
	v_add_u32_e32 v4, s4, v14
	v_mad_i64_i32 v[4:5], s[88:89], v4, s15, v[24:25]
	v_or_b32_e32 v11, 0x800, v23
	v_lshl_add_u64 v[6:7], v[4:5], 0, v[8:9]
	v_readfirstlane_b32 s88, v11
	s_mov_b32 m0, s88
	v_or_b32_e32 v15, 24, v10
	global_load_lds_dwordx4 v[6:7], off
	v_add_u32_e32 v6, s4, v15
	v_or_b32_e32 v11, 0xc00, v23
	v_mad_i64_i32 v[6:7], s[90:91], v6, s15, v[24:25]
	v_readfirstlane_b32 s89, v11
	s_lshl_b32 s8, s51, 7
	v_lshl_add_u64 v[8:9], v[6:7], 0, v[8:9]
	s_mov_b32 m0, s89
	s_ashr_i32 s73, s72, 31
	global_load_lds_dwordx4 v[8:9], off
	v_add_u32_e32 v8, s8, v10
	v_add_u32_e32 v18, 0x4000, v23
	v_mad_i64_i32 v[8:9], s[90:91], v8, s14, v[26:27]
	s_lshl_b64 s[72:73], s[72:73], 1
	v_lshl_add_u64 v[10:11], v[8:9], 0, s[72:73]
	v_lshlrev_b32_e32 v28, 4, v12
	v_readfirstlane_b32 s90, v18
	v_lshl_add_u64 v[10:11], v[10:11], 0, v[28:29]
	s_mov_b32 m0, s90
	v_add_u32_e32 v18, 0x4400, v23
	global_load_lds_dwordx4 v[10:11], off
	v_add_u32_e32 v10, s8, v13
	v_mad_i64_i32 v[10:11], s[92:93], v10, s14, v[26:27]
	v_lshl_add_u64 v[12:13], v[10:11], 0, s[72:73]
	v_readfirstlane_b32 s91, v18
	v_lshl_add_u64 v[12:13], v[12:13], 0, v[28:29]
	s_mov_b32 m0, s91
	s_add_i32 s5, s5, 1
	global_load_lds_dwordx4 v[12:13], off
	v_add_u32_e32 v12, s8, v14
	v_mad_i64_i32 v[18:19], s[92:93], v12, s14, v[26:27]
	v_add_u32_e32 v14, 0x4800, v23
	v_lshl_add_u64 v[12:13], v[18:19], 0, s[72:73]
	v_readfirstlane_b32 s92, v14
	v_lshl_add_u64 v[12:13], v[12:13], 0, v[28:29]
	s_mov_b32 m0, s92
	v_add_u32_e32 v14, 0x4c00, v23
	global_load_lds_dwordx4 v[12:13], off
	v_add_u32_e32 v12, s8, v15
	v_mad_i64_i32 v[20:21], s[94:95], v12, s14, v[26:27]
	s_cmp_lg_u32 s5, 6
	v_lshl_add_u64 v[12:13], v[20:21], 0, s[72:73]
	v_readfirstlane_b32 s93, v14
	s_cselect_b32 s96, s5, 0
	v_lshl_add_u64 v[12:13], v[12:13], 0, v[28:29]
	s_mov_b32 m0, s93
	s_lshl_b32 s72, s96, 6
	global_load_lds_dwordx4 v[12:13], off
	v_lshl_add_u64 v[12:13], v[10:11], 0, v[28:29]
	v_lshl_add_u64 v[10:11], v[18:19], 0, v[28:29]
	v_or_b32_e32 v18, s72, v16
	v_add_u32_e32 v40, 0x8000, v23
	v_ashrrev_i32_e32 v19, 31, v18
	v_lshlrev_b64 v[18:19], 1, v[18:19]
	v_readfirstlane_b32 s5, v40
	v_add_u32_e32 v40, 0x8400, v23
	v_lshl_add_u64 v[14:15], v[8:9], 0, v[28:29]
	v_lshl_add_u64 v[8:9], v[20:21], 0, v[28:29]
	v_lshl_add_u64 v[20:21], v[0:1], 0, v[18:19]
	s_mov_b32 m0, s5
	v_readfirstlane_b32 s8, v40
	v_add_u32_e32 v40, 0x8800, v23
	s_waitcnt vmcnt(0) lgkmcnt(0)
	s_barrier
	global_load_lds_dwordx4 v[20:21], off
	v_lshl_add_u64 v[20:21], v[2:3], 0, v[18:19]
	s_mov_b32 m0, s8
	v_readfirstlane_b32 s57, v40
	global_load_lds_dwordx4 v[20:21], off
	v_lshl_add_u64 v[20:21], v[4:5], 0, v[18:19]
	s_mov_b32 m0, s57
	s_ashr_i32 s73, s72, 31
	global_load_lds_dwordx4 v[20:21], off
	v_add_u32_e32 v20, 0x8c00, v23
	v_lshl_add_u64 v[18:19], v[6:7], 0, v[18:19]
	v_readfirstlane_b32 s65, v20
	v_add_u32_e32 v20, 0xc000, v23
	s_mov_b32 m0, s65
	s_lshl_b64 s[94:95], s[72:73], 1
	v_readfirstlane_b32 s71, v20
	v_add_u32_e32 v20, 0xc400, v23
	global_load_lds_dwordx4 v[18:19], off
	v_lshl_add_u64 v[18:19], v[14:15], 0, s[94:95]
	s_mov_b32 m0, s71
	v_readfirstlane_b32 s72, v20
	v_add_u32_e32 v20, 0xc800, v23
	global_load_lds_dwordx4 v[18:19], off
	v_lshl_add_u64 v[18:19], v[12:13], 0, s[94:95]
	s_mov_b32 m0, s72
	v_readfirstlane_b32 s73, v20
	v_add_u32_e32 v20, 0xcc00, v23
	global_load_lds_dwordx4 v[18:19], off
	v_lshl_add_u64 v[18:19], v[10:11], 0, s[94:95]
	s_mov_b32 m0, s73
	v_readfirstlane_b32 s85, v20
	v_bfe_u32 v22, v17, 4, 2
	global_load_lds_dwordx4 v[18:19], off
	v_lshl_add_u64 v[18:19], v[8:9], 0, s[94:95]
	s_mov_b32 m0, s85
	v_and_b32_e32 v38, 15, v17
	v_bitop3_b32 v28, v22, v17, 7 bitop3:0x78
	global_load_lds_dwordx4 v[18:19], off
	v_lshlrev_b32_e32 v18, 7, v17
	v_ashrrev_i32_e32 v39, 7, v17
	v_lshlrev_b32_e32 v23, 4, v28
	v_lshlrev_b32_e32 v28, 7, v38
	v_and_b32_e32 v80, 0x2780, v18
	v_or_b32_e32 v83, v23, v80
	v_lshl_or_b32 v28, v39, 13, v28
	ds_read_b128 v[18:21], v83 offset:16384
	v_or_b32_e32 v136, v23, v28
	ds_read_b128 v[40:43], v83 offset:18432
	ds_read_b128 v[44:47], v136
	ds_read_b128 v[48:51], v136 offset:2048
	ds_read_b128 v[56:59], v83 offset:20480
	ds_read_b128 v[64:67], v83 offset:22528
	ds_read_b128 v[88:91], v136 offset:4096
	ds_read_b128 v[92:95], v136 offset:6144
	v_and_b32_e32 v17, 7, v17
	v_bitop3_b32 v17, v22, v17, 4 bitop3:0x36
	v_lshlrev_b32_e32 v17, 4, v17
	v_or_b32_e32 v132, v17, v80
	s_waitcnt lgkmcnt(0)
	v_mfma_f32_16x16x32_bf16 v[52:55], v[18:21], v[44:47], 0
	ds_read_b128 v[108:111], v132 offset:16384
	v_or_b32_e32 v133, v17, v28
	s_add_i32 s96, s96, 1
	v_mfma_f32_16x16x32_bf16 v[60:63], v[40:43], v[44:47], 0
	s_cmp_lg_u32 s96, 6
	s_cselect_b32 s96, s96, 0
	s_lshl_b32 s94, s96, 6
	v_mfma_f32_16x16x32_bf16 v[68:71], v[56:59], v[44:47], 0
	v_or_b32_e32 v22, s94, v16
	v_ashrrev_i32_e32 v23, 31, v22
	v_lshlrev_b64 v[22:23], 1, v[22:23]
	v_mfma_f32_16x16x32_bf16 v[44:47], v[64:67], v[44:47], 0
	v_lshl_add_u64 v[80:81], v[0:1], 0, v[22:23]
	s_mov_b32 m0, s86
	s_ashr_i32 s95, s94, 31
	v_mfma_f32_16x16x32_bf16 v[72:75], v[18:21], v[48:51], 0
	s_lshl_b64 s[94:95], s[94:95], 1
	s_add_i32 s96, s96, 1
	s_cmp_lg_u32 s96, 6
	v_mfma_f32_16x16x32_bf16 v[76:79], v[40:43], v[48:51], 0
	s_cselect_b32 s96, s96, 0
	v_mfma_f32_16x16x32_bf16 v[84:87], v[56:59], v[48:51], 0
	v_mfma_f32_16x16x32_bf16 v[48:51], v[64:67], v[48:51], 0
	v_mfma_f32_16x16x32_bf16 v[96:99], v[18:21], v[88:91], 0
	v_mfma_f32_16x16x32_bf16 v[100:103], v[40:43], v[88:91], 0
	v_mfma_f32_16x16x32_bf16 v[104:107], v[56:59], v[88:91], 0
	v_mfma_f32_16x16x32_bf16 v[88:91], v[64:67], v[88:91], 0
	v_mfma_f32_16x16x32_bf16 v[18:21], v[18:21], v[92:95], 0
	v_mfma_f32_16x16x32_bf16 v[40:43], v[40:43], v[92:95], 0
	v_mfma_f32_16x16x32_bf16 v[56:59], v[56:59], v[92:95], 0
	v_mfma_f32_16x16x32_bf16 v[64:67], v[64:67], v[92:95], 0
	ds_read_b128 v[92:95], v132 offset:18432
	ds_read_b128 v[112:115], v133
	ds_read_b128 v[116:119], v133 offset:2048
	ds_read_b128 v[120:123], v132 offset:20480
	ds_read_b128 v[124:127], v132 offset:22528
	s_waitcnt lgkmcnt(3)
	v_mfma_f32_16x16x32_bf16 v[52:55], v[108:111], v[112:115], v[52:55]
	v_mfma_f32_16x16x32_bf16 v[60:63], v[92:95], v[112:115], v[60:63]
	s_waitcnt lgkmcnt(1)
	v_mfma_f32_16x16x32_bf16 v[68:71], v[120:123], v[112:115], v[68:71]
	s_waitcnt lgkmcnt(0)
	v_mfma_f32_16x16x32_bf16 v[44:47], v[124:127], v[112:115], v[44:47]
	v_mfma_f32_16x16x32_bf16 v[72:75], v[108:111], v[116:119], v[72:75]
	v_mfma_f32_16x16x32_bf16 v[76:79], v[92:95], v[116:119], v[76:79]
	v_mfma_f32_16x16x32_bf16 v[84:87], v[120:123], v[116:119], v[84:87]
	v_mfma_f32_16x16x32_bf16 v[48:51], v[124:127], v[116:119], v[48:51]
	ds_read_b128 v[112:115], v133 offset:4096
	ds_read_b128 v[116:119], v133 offset:6144
	s_waitcnt vmcnt(0) lgkmcnt(0)
	s_barrier
	global_load_lds_dwordx4 v[80:81], off
	v_lshl_add_u64 v[80:81], v[2:3], 0, v[22:23]
	s_mov_b32 m0, s87
	v_mfma_f32_16x16x32_bf16 v[96:99], v[108:111], v[112:115], v[96:99]
	global_load_lds_dwordx4 v[80:81], off
	v_lshl_add_u64 v[80:81], v[4:5], 0, v[22:23]
	s_mov_b32 m0, s88
	v_lshl_add_u64 v[22:23], v[6:7], 0, v[22:23]
	global_load_lds_dwordx4 v[80:81], off
	s_mov_b32 m0, s89
	v_mfma_f32_16x16x32_bf16 v[100:103], v[92:95], v[112:115], v[100:103]
	global_load_lds_dwordx4 v[22:23], off
	v_lshl_add_u64 v[22:23], v[14:15], 0, s[94:95]
	s_mov_b32 m0, s90
	v_mfma_f32_16x16x32_bf16 v[104:107], v[120:123], v[112:115], v[104:107]
	global_load_lds_dwordx4 v[22:23], off
	v_lshl_add_u64 v[22:23], v[12:13], 0, s[94:95]
	s_mov_b32 m0, s91
	v_mfma_f32_16x16x32_bf16 v[88:91], v[124:127], v[112:115], v[88:91]
	global_load_lds_dwordx4 v[22:23], off
	v_lshl_add_u64 v[22:23], v[10:11], 0, s[94:95]
	s_mov_b32 m0, s92
	v_mfma_f32_16x16x32_bf16 v[18:21], v[108:111], v[116:119], v[18:21]
	global_load_lds_dwordx4 v[22:23], off
	v_lshl_add_u64 v[22:23], v[8:9], 0, s[94:95]
	s_mov_b32 m0, s93
	v_mfma_f32_16x16x32_bf16 v[40:43], v[92:95], v[116:119], v[40:43]
	global_load_lds_dwordx4 v[22:23], off
	ds_read_b128 v[92:95], v83 offset:49152
	v_mfma_f32_16x16x32_bf16 v[56:59], v[120:123], v[116:119], v[56:59]
	s_lshl_b32 s94, s96, 6
	v_or_b32_e32 v22, s94, v16
	v_ashrrev_i32_e32 v23, 31, v22
	v_mfma_f32_16x16x32_bf16 v[64:67], v[124:127], v[116:119], v[64:67]
	ds_read_b128 v[108:111], v83 offset:51200
	ds_read_b128 v[112:115], v136 offset:32768
	ds_read_b128 v[116:119], v136 offset:34816
	ds_read_b128 v[120:123], v83 offset:53248
	ds_read_b128 v[124:127], v83 offset:55296
	s_waitcnt lgkmcnt(0)
	v_mfma_f32_16x16x32_bf16 v[52:55], v[92:95], v[112:115], v[52:55]
	v_lshlrev_b64 v[22:23], 1, v[22:23]
	v_lshl_add_u64 v[80:81], v[0:1], 0, v[22:23]
	s_mov_b32 m0, s5
	v_mfma_f32_16x16x32_bf16 v[60:63], v[108:111], v[112:115], v[60:63]
	s_ashr_i32 s95, s94, 31
	s_lshl_b64 s[94:95], s[94:95], 1
	s_add_i32 s96, s96, 1
	v_mfma_f32_16x16x32_bf16 v[68:71], v[120:123], v[112:115], v[68:71]
	s_cmp_lg_u32 s96, 6
	s_cselect_b32 s96, s96, 0
	v_mfma_f32_16x16x32_bf16 v[44:47], v[124:127], v[112:115], v[44:47]
	v_mfma_f32_16x16x32_bf16 v[72:75], v[92:95], v[116:119], v[72:75]
	v_mfma_f32_16x16x32_bf16 v[76:79], v[108:111], v[116:119], v[76:79]
	v_mfma_f32_16x16x32_bf16 v[84:87], v[120:123], v[116:119], v[84:87]
	v_mfma_f32_16x16x32_bf16 v[48:51], v[124:127], v[116:119], v[48:51]
	ds_read_b128 v[112:115], v136 offset:36864
	ds_read_b128 v[116:119], v136 offset:38912
	s_waitcnt lgkmcnt(1)
	v_mfma_f32_16x16x32_bf16 v[96:99], v[92:95], v[112:115], v[96:99]
	v_mfma_f32_16x16x32_bf16 v[100:103], v[108:111], v[112:115], v[100:103]
	v_mfma_f32_16x16x32_bf16 v[104:107], v[120:123], v[112:115], v[104:107]
	v_mfma_f32_16x16x32_bf16 v[88:91], v[124:127], v[112:115], v[88:91]
	s_waitcnt lgkmcnt(0)
	v_mfma_f32_16x16x32_bf16 v[18:21], v[92:95], v[116:119], v[18:21]
	ds_read_b128 v[92:95], v132 offset:49152
	v_mfma_f32_16x16x32_bf16 v[40:43], v[108:111], v[116:119], v[40:43]
	v_mfma_f32_16x16x32_bf16 v[56:59], v[120:123], v[116:119], v[56:59]
	v_mfma_f32_16x16x32_bf16 v[64:67], v[124:127], v[116:119], v[64:67]
	ds_read_b128 v[108:111], v132 offset:51200
	ds_read_b128 v[112:115], v133 offset:32768
	ds_read_b128 v[116:119], v133 offset:34816
	ds_read_b128 v[120:123], v132 offset:53248
	ds_read_b128 v[124:127], v132 offset:55296
	s_waitcnt lgkmcnt(3)
	v_mfma_f32_16x16x32_bf16 v[52:55], v[92:95], v[112:115], v[52:55]
	v_mfma_f32_16x16x32_bf16 v[60:63], v[108:111], v[112:115], v[60:63]
	s_waitcnt lgkmcnt(1)
	v_mfma_f32_16x16x32_bf16 v[68:71], v[120:123], v[112:115], v[68:71]
	s_waitcnt lgkmcnt(0)
	v_mfma_f32_16x16x32_bf16 v[44:47], v[124:127], v[112:115], v[44:47]
	v_mfma_f32_16x16x32_bf16 v[72:75], v[92:95], v[116:119], v[72:75]
	v_mfma_f32_16x16x32_bf16 v[76:79], v[108:111], v[116:119], v[76:79]
	v_mfma_f32_16x16x32_bf16 v[84:87], v[120:123], v[116:119], v[84:87]
	v_mfma_f32_16x16x32_bf16 v[48:51], v[124:127], v[116:119], v[48:51]
	ds_read_b128 v[112:115], v133 offset:36864
	ds_read_b128 v[116:119], v133 offset:38912
	s_waitcnt vmcnt(0) lgkmcnt(0)
	s_barrier
	global_load_lds_dwordx4 v[80:81], off
	v_lshl_add_u64 v[80:81], v[2:3], 0, v[22:23]
	s_mov_b32 m0, s8
	v_mfma_f32_16x16x32_bf16 v[96:99], v[92:95], v[112:115], v[96:99]
	global_load_lds_dwordx4 v[80:81], off
	v_lshl_add_u64 v[80:81], v[4:5], 0, v[22:23]
	s_mov_b32 m0, s57
	v_lshl_add_u64 v[22:23], v[6:7], 0, v[22:23]
	global_load_lds_dwordx4 v[80:81], off
	s_mov_b32 m0, s65
	v_mfma_f32_16x16x32_bf16 v[100:103], v[108:111], v[112:115], v[100:103]
	global_load_lds_dwordx4 v[22:23], off
	v_lshl_add_u64 v[22:23], v[14:15], 0, s[94:95]
	s_mov_b32 m0, s71
	v_mfma_f32_16x16x32_bf16 v[104:107], v[120:123], v[112:115], v[104:107]
	global_load_lds_dwordx4 v[22:23], off
	v_lshl_add_u64 v[22:23], v[12:13], 0, s[94:95]
	s_mov_b32 m0, s72
	v_mfma_f32_16x16x32_bf16 v[88:91], v[124:127], v[112:115], v[88:91]
	global_load_lds_dwordx4 v[22:23], off
	v_lshl_add_u64 v[22:23], v[10:11], 0, s[94:95]
	s_mov_b32 m0, s73
	v_mfma_f32_16x16x32_bf16 v[18:21], v[92:95], v[116:119], v[18:21]
	global_load_lds_dwordx4 v[22:23], off
	v_lshl_add_u64 v[22:23], v[8:9], 0, s[94:95]
	s_mov_b32 m0, s85
	v_mfma_f32_16x16x32_bf16 v[40:43], v[108:111], v[116:119], v[40:43]
	global_load_lds_dwordx4 v[22:23], off
	ds_read_b128 v[92:95], v83 offset:16384
	v_mfma_f32_16x16x32_bf16 v[56:59], v[120:123], v[116:119], v[56:59]
	s_lshl_b32 s94, s96, 6
	v_or_b32_e32 v22, s94, v16
	v_ashrrev_i32_e32 v23, 31, v22
	v_mfma_f32_16x16x32_bf16 v[64:67], v[124:127], v[116:119], v[64:67]
	ds_read_b128 v[108:111], v83 offset:18432
	ds_read_b128 v[112:115], v136
	ds_read_b128 v[116:119], v136 offset:2048
	ds_read_b128 v[120:123], v83 offset:20480
	ds_read_b128 v[124:127], v83 offset:22528
	s_waitcnt lgkmcnt(0)
	v_mfma_f32_16x16x32_bf16 v[52:55], v[92:95], v[112:115], v[52:55]
	v_lshlrev_b64 v[22:23], 1, v[22:23]
	v_lshl_add_u64 v[80:81], v[0:1], 0, v[22:23]
	s_mov_b32 m0, s86
	v_mfma_f32_16x16x32_bf16 v[60:63], v[108:111], v[112:115], v[60:63]
	s_ashr_i32 s95, s94, 31
	s_add_i32 s96, s96, 1
	v_mfma_f32_16x16x32_bf16 v[68:71], v[120:123], v[112:115], v[68:71]
	v_mfma_f32_16x16x32_bf16 v[44:47], v[124:127], v[112:115], v[44:47]
	v_mfma_f32_16x16x32_bf16 v[72:75], v[92:95], v[116:119], v[72:75]
	v_mfma_f32_16x16x32_bf16 v[76:79], v[108:111], v[116:119], v[76:79]
	v_mfma_f32_16x16x32_bf16 v[84:87], v[120:123], v[116:119], v[84:87]
	v_mfma_f32_16x16x32_bf16 v[48:51], v[124:127], v[116:119], v[48:51]
	ds_read_b128 v[112:115], v136 offset:4096
	ds_read_b128 v[116:119], v136 offset:6144
	s_waitcnt lgkmcnt(1)
	v_mfma_f32_16x16x32_bf16 v[96:99], v[92:95], v[112:115], v[96:99]
	v_mfma_f32_16x16x32_bf16 v[100:103], v[108:111], v[112:115], v[100:103]
	v_mfma_f32_16x16x32_bf16 v[104:107], v[120:123], v[112:115], v[104:107]
	v_mfma_f32_16x16x32_bf16 v[88:91], v[124:127], v[112:115], v[88:91]
	s_waitcnt lgkmcnt(0)
	v_mfma_f32_16x16x32_bf16 v[18:21], v[92:95], v[116:119], v[18:21]
	ds_read_b128 v[92:95], v132 offset:16384
	v_mfma_f32_16x16x32_bf16 v[40:43], v[108:111], v[116:119], v[40:43]
	v_mfma_f32_16x16x32_bf16 v[56:59], v[120:123], v[116:119], v[56:59]
	v_mfma_f32_16x16x32_bf16 v[64:67], v[124:127], v[116:119], v[64:67]
	ds_read_b128 v[108:111], v132 offset:18432
	ds_read_b128 v[112:115], v133
	ds_read_b128 v[116:119], v133 offset:2048
	ds_read_b128 v[120:123], v132 offset:20480
	ds_read_b128 v[124:127], v132 offset:22528
	s_waitcnt lgkmcnt(3)
	v_mfma_f32_16x16x32_bf16 v[52:55], v[92:95], v[112:115], v[52:55]
	v_mfma_f32_16x16x32_bf16 v[60:63], v[108:111], v[112:115], v[60:63]
	s_waitcnt lgkmcnt(1)
	v_mfma_f32_16x16x32_bf16 v[68:71], v[120:123], v[112:115], v[68:71]
	s_waitcnt lgkmcnt(0)
	v_mfma_f32_16x16x32_bf16 v[44:47], v[124:127], v[112:115], v[44:47]
	v_mfma_f32_16x16x32_bf16 v[72:75], v[92:95], v[116:119], v[72:75]
	v_mfma_f32_16x16x32_bf16 v[76:79], v[108:111], v[116:119], v[76:79]
	v_mfma_f32_16x16x32_bf16 v[84:87], v[120:123], v[116:119], v[84:87]
	v_mfma_f32_16x16x32_bf16 v[48:51], v[124:127], v[116:119], v[48:51]
	ds_read_b128 v[112:115], v133 offset:4096
	ds_read_b128 v[116:119], v133 offset:6144
	s_waitcnt vmcnt(0) lgkmcnt(0)
	s_barrier
	global_load_lds_dwordx4 v[80:81], off
	v_lshl_add_u64 v[80:81], v[2:3], 0, v[22:23]
	s_mov_b32 m0, s87
	s_lshl_b64 s[86:87], s[94:95], 1
	global_load_lds_dwordx4 v[80:81], off
	v_lshl_add_u64 v[80:81], v[4:5], 0, v[22:23]
	s_mov_b32 m0, s88
	v_lshl_add_u64 v[22:23], v[6:7], 0, v[22:23]
	global_load_lds_dwordx4 v[80:81], off
	s_mov_b32 m0, s89
	v_mfma_f32_16x16x32_bf16 v[96:99], v[92:95], v[112:115], v[96:99]
	global_load_lds_dwordx4 v[22:23], off
	v_lshl_add_u64 v[22:23], v[14:15], 0, s[86:87]
	s_mov_b32 m0, s90
	v_mfma_f32_16x16x32_bf16 v[100:103], v[108:111], v[112:115], v[100:103]
	global_load_lds_dwordx4 v[22:23], off
	v_lshl_add_u64 v[22:23], v[12:13], 0, s[86:87]
	s_mov_b32 m0, s91
	v_mfma_f32_16x16x32_bf16 v[104:107], v[120:123], v[112:115], v[104:107]
	global_load_lds_dwordx4 v[22:23], off
	v_lshl_add_u64 v[22:23], v[10:11], 0, s[86:87]
	s_mov_b32 m0, s92
	v_mfma_f32_16x16x32_bf16 v[88:91], v[124:127], v[112:115], v[88:91]
	global_load_lds_dwordx4 v[22:23], off
	v_lshl_add_u64 v[22:23], v[8:9], 0, s[86:87]
	s_mov_b32 m0, s93
	v_mfma_f32_16x16x32_bf16 v[18:21], v[92:95], v[116:119], v[18:21]
	global_load_lds_dwordx4 v[22:23], off
	ds_read_b128 v[92:95], v83 offset:49152
	v_mfma_f32_16x16x32_bf16 v[40:43], v[108:111], v[116:119], v[40:43]
	s_lshl_b32 s86, s96, 6
	s_cmp_lg_u32 s96, 6
	s_cselect_b32 s86, s86, 0
	v_mfma_f32_16x16x32_bf16 v[56:59], v[120:123], v[116:119], v[56:59]
	v_or_b32_e32 v16, s86, v16
	v_lshlrev_b32_e32 v28, 1, v16
	v_lshl_add_u64 v[0:1], v[0:1], 0, v[28:29]
	v_mfma_f32_16x16x32_bf16 v[64:67], v[124:127], v[116:119], v[64:67]
	ds_read_b128 v[108:111], v83 offset:51200
	ds_read_b128 v[112:115], v136 offset:32768
	ds_read_b128 v[116:119], v136 offset:34816
	ds_read_b128 v[120:123], v83 offset:53248
	ds_read_b128 v[124:127], v83 offset:55296
	s_waitcnt lgkmcnt(0)
	v_mfma_f32_16x16x32_bf16 v[52:55], v[92:95], v[112:115], v[52:55]
	s_mov_b32 m0, s5
	v_mfma_f32_16x16x32_bf16 v[60:63], v[108:111], v[112:115], v[60:63]
	v_mfma_f32_16x16x32_bf16 v[68:71], v[120:123], v[112:115], v[68:71]
	v_mfma_f32_16x16x32_bf16 v[44:47], v[124:127], v[112:115], v[44:47]
	v_mfma_f32_16x16x32_bf16 v[72:75], v[92:95], v[116:119], v[72:75]
	v_mfma_f32_16x16x32_bf16 v[76:79], v[108:111], v[116:119], v[76:79]
	v_mfma_f32_16x16x32_bf16 v[84:87], v[120:123], v[116:119], v[84:87]
	v_mfma_f32_16x16x32_bf16 v[48:51], v[124:127], v[116:119], v[48:51]
	ds_read_b128 v[112:115], v136 offset:36864
	ds_read_b128 v[116:119], v136 offset:38912
	s_waitcnt lgkmcnt(1)
	v_mfma_f32_16x16x32_bf16 v[96:99], v[92:95], v[112:115], v[96:99]
	v_mfma_f32_16x16x32_bf16 v[100:103], v[108:111], v[112:115], v[100:103]
	v_mfma_f32_16x16x32_bf16 v[104:107], v[120:123], v[112:115], v[104:107]
	v_mfma_f32_16x16x32_bf16 v[88:91], v[124:127], v[112:115], v[88:91]
	s_waitcnt lgkmcnt(0)
	v_mfma_f32_16x16x32_bf16 v[18:21], v[92:95], v[116:119], v[18:21]
	ds_read_b128 v[92:95], v132 offset:49152
	v_mfma_f32_16x16x32_bf16 v[40:43], v[108:111], v[116:119], v[40:43]
	v_mfma_f32_16x16x32_bf16 v[56:59], v[120:123], v[116:119], v[56:59]
	v_mfma_f32_16x16x32_bf16 v[64:67], v[124:127], v[116:119], v[64:67]
	ds_read_b128 v[108:111], v132 offset:51200
	ds_read_b128 v[112:115], v133 offset:32768
	ds_read_b128 v[116:119], v133 offset:34816
	ds_read_b128 v[120:123], v132 offset:53248
	ds_read_b128 v[124:127], v132 offset:55296
	s_waitcnt lgkmcnt(3)
	v_mfma_f32_16x16x32_bf16 v[52:55], v[92:95], v[112:115], v[52:55]
	v_mfma_f32_16x16x32_bf16 v[60:63], v[108:111], v[112:115], v[60:63]
	s_waitcnt lgkmcnt(1)
	v_mfma_f32_16x16x32_bf16 v[68:71], v[120:123], v[112:115], v[68:71]
	s_waitcnt lgkmcnt(0)
	v_mfma_f32_16x16x32_bf16 v[44:47], v[124:127], v[112:115], v[44:47]
	v_mfma_f32_16x16x32_bf16 v[72:75], v[92:95], v[116:119], v[72:75]
	v_mfma_f32_16x16x32_bf16 v[76:79], v[108:111], v[116:119], v[76:79]
	v_mfma_f32_16x16x32_bf16 v[84:87], v[120:123], v[116:119], v[84:87]
	v_mfma_f32_16x16x32_bf16 v[48:51], v[124:127], v[116:119], v[48:51]
	ds_read_b128 v[112:115], v133 offset:36864
	ds_read_b128 v[116:119], v133 offset:38912
	s_waitcnt vmcnt(0) lgkmcnt(0)
	s_barrier
	global_load_lds_dwordx4 v[0:1], off
	v_lshl_add_u64 v[0:1], v[2:3], 0, v[28:29]
	s_mov_b32 m0, s8
	s_lshl_b32 s8, s86, 1
	global_load_lds_dwordx4 v[0:1], off
	v_lshl_add_u64 v[0:1], v[4:5], 0, v[28:29]
	s_mov_b32 m0, s57
	v_mfma_f32_16x16x32_bf16 v[96:99], v[92:95], v[112:115], v[96:99]
	global_load_lds_dwordx4 v[0:1], off
	v_lshl_add_u64 v[0:1], v[6:7], 0, v[28:29]
	s_mov_b32 m0, s65
	v_mfma_f32_16x16x32_bf16 v[100:103], v[108:111], v[112:115], v[100:103]
	global_load_lds_dwordx4 v[0:1], off
	v_lshl_add_u64 v[0:1], v[14:15], 0, s[8:9]
	s_mov_b32 m0, s71
	v_mfma_f32_16x16x32_bf16 v[18:21], v[92:95], v[116:119], v[18:21]
	global_load_lds_dwordx4 v[0:1], off
	v_lshl_add_u64 v[0:1], v[12:13], 0, s[8:9]
	s_mov_b32 m0, s72
	v_mfma_f32_16x16x32_bf16 v[40:43], v[108:111], v[116:119], v[40:43]
	global_load_lds_dwordx4 v[0:1], off
	v_lshl_add_u64 v[0:1], v[10:11], 0, s[8:9]
	s_mov_b32 m0, s73
	v_mfma_f32_16x16x32_bf16 v[4:7], v[124:127], v[116:119], v[64:67]
	global_load_lds_dwordx4 v[0:1], off
	v_lshl_add_u64 v[0:1], v[8:9], 0, s[8:9]
	s_mov_b32 m0, s85
	v_mfma_f32_16x16x32_bf16 v[104:107], v[120:123], v[112:115], v[104:107]
	global_load_lds_dwordx4 v[0:1], off
	ds_read_b128 v[0:3], v83 offset:16384
	ds_read_b128 v[8:11], v83 offset:18432
	ds_read_b128 v[12:15], v136
	ds_read_b128 v[64:67], v136 offset:2048
	ds_read_b128 v[92:95], v83 offset:20480
	ds_read_b128 v[108:111], v83 offset:22528
	s_waitcnt lgkmcnt(0)
	v_mfma_f32_16x16x32_bf16 v[52:55], v[0:3], v[12:15], v[52:55]
	v_lshl_add_u32 v28, v39, 6, s4
	v_or_b32_e32 v38, v28, v38
	v_ashrrev_i32_e32 v39, 31, v38
	v_mfma_f32_16x16x32_bf16 v[60:63], v[8:11], v[12:15], v[60:63]
	v_lshl_add_u64 v[38:39], v[38:39], 2, s[6:7]
	v_mfma_f32_16x16x32_bf16 v[68:71], v[92:95], v[12:15], v[68:71]
	v_mfma_f32_16x16x32_bf16 v[12:15], v[108:111], v[12:15], v[44:47]
	v_mfma_f32_16x16x32_bf16 v[44:47], v[0:3], v[64:67], v[72:75]
	v_mfma_f32_16x16x32_bf16 v[72:75], v[8:11], v[64:67], v[76:79]
	v_mfma_f32_16x16x32_bf16 v[76:79], v[92:95], v[64:67], v[84:87]
	v_mfma_f32_16x16x32_bf16 v[48:51], v[108:111], v[64:67], v[48:51]
	ds_read_b128 v[64:67], v136 offset:4096
	s_nop 0
	ds_read_b128 v[84:87], v136 offset:6144
	v_mfma_f32_16x16x32_bf16 v[88:91], v[124:127], v[112:115], v[88:91]
	v_mfma_f32_16x16x32_bf16 v[56:59], v[120:123], v[116:119], v[56:59]
	s_waitcnt lgkmcnt(1)
	v_mfma_f32_16x16x32_bf16 v[96:99], v[0:3], v[64:67], v[96:99]
	v_mfma_f32_16x16x32_bf16 v[100:103], v[8:11], v[64:67], v[100:103]
	v_mfma_f32_16x16x32_bf16 v[104:107], v[92:95], v[64:67], v[104:107]
	v_mfma_f32_16x16x32_bf16 v[64:67], v[108:111], v[64:67], v[88:91]
	s_waitcnt lgkmcnt(0)
	v_mfma_f32_16x16x32_bf16 v[88:91], v[0:3], v[84:87], v[18:21]
	v_mfma_f32_16x16x32_bf16 v[40:43], v[8:11], v[84:87], v[40:43]
	v_mfma_f32_16x16x32_bf16 v[56:59], v[92:95], v[84:87], v[56:59]
	ds_read_b128 v[92:95], v132 offset:16384
	v_mfma_f32_16x16x32_bf16 v[84:87], v[108:111], v[84:87], v[4:7]
	ds_read_b128 v[108:111], v132 offset:18432
	ds_read_b128 v[0:3], v133
	s_nop 0
	ds_read_b128 v[4:7], v133 offset:2048
	ds_read_b128 v[112:115], v132 offset:20480
	ds_read_b128 v[116:119], v132 offset:22528
	ds_read_b128 v[124:127], v133 offset:4096
	ds_read_b128 v[128:131], v133 offset:6144
	s_waitcnt lgkmcnt(5)
	v_mfma_f32_16x16x32_bf16 v[52:55], v[92:95], v[0:3], v[52:55]
	s_waitcnt vmcnt(0) lgkmcnt(0)
	s_barrier
	v_mfma_f32_16x16x32_bf16 v[60:63], v[108:111], v[0:3], v[60:63]
	v_mfma_f32_16x16x32_bf16 v[68:71], v[112:115], v[0:3], v[68:71]
	v_mfma_f32_16x16x32_bf16 v[120:123], v[116:119], v[0:3], v[12:15]
	ds_read_b128 v[0:3], v132 offset:55296
	ds_read_b128 v[8:11], v132 offset:53248
	v_mfma_f32_16x16x32_bf16 v[44:47], v[92:95], v[4:7], v[44:47]
	v_mfma_f32_16x16x32_bf16 v[72:75], v[108:111], v[4:7], v[72:75]
	v_mfma_f32_16x16x32_bf16 v[76:79], v[112:115], v[4:7], v[76:79]
	v_mfma_f32_16x16x32_bf16 v[48:51], v[116:119], v[4:7], v[48:51]
	ds_read_b128 v[4:7], v133 offset:38912
	ds_read_b128 v[20:23], v133 offset:36864
	ds_read_b128 v[12:15], v132 offset:51200
	ds_read_b128 v[16:19], v132 offset:49152
	v_mfma_f32_16x16x32_bf16 v[96:99], v[92:95], v[124:127], v[96:99]
	v_mfma_f32_16x16x32_bf16 v[100:103], v[108:111], v[124:127], v[100:103]
	v_mfma_f32_16x16x32_bf16 v[104:107], v[112:115], v[124:127], v[104:107]
	v_mfma_f32_16x16x32_bf16 v[64:67], v[116:119], v[124:127], v[64:67]
	ds_read_b128 v[124:127], v133 offset:34816
	ds_read_b128 v[132:135], v133 offset:32768
	ds_read_b128 v[140:143], v83 offset:55296
	ds_read_b128 v[144:147], v83 offset:53248
	v_mfma_f32_16x16x32_bf16 v[88:91], v[92:95], v[128:131], v[88:91]
	ds_read_b128 v[92:95], v136 offset:38912
	ds_read_b128 v[148:151], v136 offset:36864
	ds_read_b128 v[152:155], v83 offset:51200
	ds_read_b128 v[156:159], v83 offset:49152
	v_mfma_f32_16x16x32_bf16 v[40:43], v[108:111], v[128:131], v[40:43]
	ds_read_b128 v[108:111], v136 offset:34816
	ds_read_b128 v[160:163], v136 offset:32768
	s_waitcnt lgkmcnt(0)
	s_barrier
	global_load_dword v28, v[38:39], off
	global_load_dword v80, v[38:39], off offset:64
	global_load_dword v81, v[38:39], off offset:128
	v_mfma_f32_16x16x32_bf16 v[56:59], v[112:115], v[128:131], v[56:59]
	global_load_dword v38, v[38:39], off offset:192
	s_waitcnt vmcnt(3)
	v_fmamk_f32 v28, v28, 0x3b2aaaab, v31
	v_mul_f32_e32 v39, 0x4b800000, v28
	v_cmp_gt_f32_e32 vcc, s13, v28
	v_mfma_f32_16x16x32_bf16 v[84:87], v[116:119], v[128:131], v[84:87]
	s_waitcnt vmcnt(0)
	v_fmamk_f32 v38, v38, 0x3b2aaaab, v31
	v_cndmask_b32_e32 v28, v28, v39, vcc
	v_fmamk_f32 v39, v80, 0x3b2aaaab, v31
	v_mul_f32_e32 v80, 0x4b800000, v39
	v_cmp_gt_f32_e64 s[4:5], s13, v39
	v_rsq_f32_e32 v28, v28
	v_mfma_f32_16x16x32_bf16 v[44:47], v[156:159], v[108:111], v[44:47]
	v_cndmask_b32_e64 v39, v39, v80, s[4:5]
	v_rsq_f32_e32 v39, v39
	v_mul_f32_e32 v80, 0x45800000, v28
	v_cndmask_b32_e32 v28, v28, v80, vcc
	v_mfma_f32_16x16x32_bf16 v[72:75], v[152:155], v[108:111], v[72:75]
	v_mul_f32_e32 v80, 0x45800000, v39
	v_cndmask_b32_e64 v80, v39, v80, s[4:5]
	v_fmamk_f32 v39, v81, 0x3b2aaaab, v31
	v_mul_f32_e32 v81, 0x4b800000, v39
	v_cmp_gt_f32_e32 vcc, s13, v39
	v_cmp_gt_f32_e64 s[4:5], s13, v38
	v_mfma_f32_16x16x32_bf16 v[76:79], v[144:147], v[108:111], v[76:79]
	v_cndmask_b32_e32 v39, v39, v81, vcc
	v_mul_f32_e32 v81, 0x4b800000, v38
	v_rsq_f32_e32 v39, v39
	v_cndmask_b32_e64 v38, v38, v81, s[4:5]
	v_rsq_f32_e32 v38, v38
	v_mfma_f32_16x16x32_bf16 v[48:51], v[140:143], v[108:111], v[48:51]
	v_mul_f32_e32 v81, 0x45800000, v39
	v_cndmask_b32_e32 v108, v39, v81, vcc
	v_mul_f32_e32 v39, 0x45800000, v38
	v_mov_b32_e32 v81, v138
	v_cndmask_b32_e64 v110, v38, v39, s[4:5]
	v_mfma_f32_16x16x32_bf16 v[38:41], v[152:155], v[92:95], v[40:43]
	v_cmp_lt_i32_e32 vcc, v34, v35
	v_lshrrev_b32_e32 v83, 1, v81
	v_mfma_f32_16x16x32_bf16 v[88:91], v[156:159], v[92:95], v[88:91]
	v_and_b32_e32 v43, 15, v81
	v_and_b32_e32 v42, 64, v81
	v_and_or_b32 v43, v83, s31, v43
	v_and_b32_e32 v83, 48, v81
	v_lshl_or_b32 v42, v42, 2, v83
	v_mfma_f32_16x16x32_bf16 v[56:59], v[144:147], v[92:95], v[56:59]
	v_mfma_f32_16x16x32_bf16 v[84:87], v[140:143], v[92:95], v[84:87]
	v_mad_u64_u32 v[92:93], s[4:5], v43, s34, v[42:43]
	s_mul_i32 s4, s51, 0x60
	v_mfma_f32_16x16x32_bf16 v[42:45], v[16:19], v[124:127], v[44:47]
	s_ashr_i32 s5, s4, 31
	s_lshl_b64 s[4:5], s[4:5], 1
	s_add_u32 s4, s78, s4
	v_mfma_f32_16x16x32_bf16 v[52:55], v[156:159], v[160:163], v[52:55]
	s_addc_u32 s5, s79, s5
	s_nop 2
	v_pk_mul_f32 v[44:45], v[44:45], v[80:81] op_sel_hi:[1,0]
	v_pk_mul_f32 v[42:43], v[42:43], v[80:81] op_sel_hi:[1,0]
	ds_write_b128 v92, v[42:45] offset:8448
	v_mfma_f32_16x16x32_bf16 v[42:45], v[12:15], v[124:127], v[72:75]
	s_lshl_b32 s8, s50, 7
	s_and_b32 s8, s8, 0xfffffc00
	s_or_b32 s8, s8, s30
	v_mfma_f32_16x16x32_bf16 v[52:55], v[16:19], v[132:135], v[52:55]
	v_mfma_f32_16x16x32_bf16 v[60:63], v[152:155], v[160:163], v[60:63]
	s_nop 2
	v_mul_f32_e64 v44, v44, v80
	v_mul_f32_e64 v45, v45, v80
	v_pk_mul_f32 v[42:43], v[42:43], v[80:81] op_sel_hi:[1,0]
	ds_write_b128 v92, v[42:45] offset:8512
	v_mfma_f32_16x16x32_bf16 v[42:45], v[8:11], v[124:127], v[76:79]
	v_mul_f32_e64 v54, v54, v28
	v_mul_f32_e64 v55, v55, v28
	v_pk_mul_f32 v[52:53], v[52:53], v[28:29] op_sel_hi:[1,0]
	ds_write_b128 v92, v[52:55]
	v_mfma_f32_16x16x32_bf16 v[96:99], v[156:159], v[148:151], v[96:99]
	v_mfma_f32_16x16x32_bf16 v[52:55], v[12:15], v[132:135], v[60:63]
	s_nop 1
	v_mul_f32_e64 v44, v44, v80
	v_mul_f32_e64 v45, v45, v80
	v_pk_mul_f32 v[42:43], v[42:43], v[80:81] op_sel_hi:[1,0]
	ds_write_b128 v92, v[42:45] offset:8576
	v_mfma_f32_16x16x32_bf16 v[42:45], v[0:3], v[124:127], v[48:51]
	v_mfma_f32_16x16x32_bf16 v[68:71], v[144:147], v[160:163], v[68:71]
	v_mul_f32_e64 v54, v54, v28
	v_mul_f32_e64 v55, v55, v28
	s_nop 4
	v_pk_mul_f32 v[44:45], v[44:45], v[80:81] op_sel_hi:[1,0]
	v_pk_mul_f32 v[42:43], v[42:43], v[80:81] op_sel_hi:[1,0]
	ds_write_b128 v92, v[42:45] offset:8640
	v_mfma_f32_16x16x32_bf16 v[42:45], v[16:19], v[20:23], v[96:99]
	v_mul_f32_e64 v52, v52, v28
	v_mul_f32_e64 v53, v53, v28
	ds_write_b128 v92, v[52:55] offset:64
	v_mfma_f32_16x16x32_bf16 v[100:103], v[152:155], v[148:151], v[100:103]
	v_mfma_f32_16x16x32_bf16 v[52:55], v[8:11], v[132:135], v[68:71]
	s_nop 2
	v_mul_f32_e64 v44, v44, v108
	v_mul_f32_e64 v45, v45, v108
	v_pk_mul_f32 v[42:43], v[42:43], v[108:109] op_sel_hi:[1,0]
	ds_write_b128 v92, v[42:45] offset:16896
	v_mfma_f32_16x16x32_bf16 v[42:45], v[12:15], v[20:23], v[100:103]
	v_mfma_f32_16x16x32_bf16 v[112:115], v[140:143], v[160:163], v[120:123]
	v_mul_f32_e64 v54, v54, v28
	v_mul_f32_e64 v55, v55, v28
	v_pk_mul_f32 v[52:53], v[52:53], v[28:29] op_sel_hi:[1,0]
	s_nop 3
	v_pk_mul_f32 v[44:45], v[44:45], v[108:109] op_sel_hi:[1,0]
	v_mfma_f32_16x16x32_bf16 v[104:107], v[144:147], v[148:151], v[104:107]
	v_mul_f32_e64 v42, v42, v108
	v_mul_f32_e64 v43, v43, v108
	ds_write_b128 v92, v[52:55] offset:128
	ds_write_b128 v92, v[42:45] offset:16960
	v_mfma_f32_16x16x32_bf16 v[64:67], v[140:143], v[148:151], v[64:67]
	v_mfma_f32_16x16x32_bf16 v[52:55], v[0:3], v[132:135], v[112:115]
	v_mfma_f32_16x16x32_bf16 v[42:45], v[8:11], v[20:23], v[104:107]
	v_mfma_f32_16x16x32_bf16 v[20:23], v[0:3], v[20:23], v[64:67]
	s_nop 5
	v_mul_f32_e64 v54, v54, v28
	v_mul_f32_e64 v55, v55, v28
	v_pk_mul_f32 v[52:53], v[52:53], v[28:29] op_sel_hi:[1,0]
	v_pk_mul_f32 v[44:45], v[44:45], v[108:109] op_sel_hi:[1,0]
	v_mfma_f32_16x16x32_bf16 v[0:3], v[0:3], v[4:7], v[84:87]
	v_mul_f32_e64 v42, v42, v108
	v_mul_f32_e64 v43, v43, v108
	v_pk_mul_f32 v[22:23], v[22:23], v[108:109] op_sel_hi:[1,0]
	v_pk_mul_f32 v[20:21], v[20:21], v[108:109] op_sel_hi:[1,0]
	v_mfma_f32_16x16x32_bf16 v[16:19], v[16:19], v[4:7], v[88:91]
	ds_write_b128 v92, v[20:23] offset:17088
	s_nop 1
	v_pk_mul_f32 v[2:3], v[2:3], v[110:111] op_sel_hi:[1,0]
	v_pk_mul_f32 v[0:1], v[0:1], v[110:111] op_sel_hi:[1,0]
	v_mfma_f32_16x16x32_bf16 v[12:15], v[12:15], v[4:7], v[38:41]
	ds_write_b128 v92, v[0:3] offset:25536
	v_cndmask_b32_e32 v0, v33, v34, vcc
	v_cmp_lt_i32_e32 vcc, v36, v35
	v_mfma_f32_16x16x32_bf16 v[8:11], v[8:11], v[4:7], v[56:59]
	v_and_b32_e32 v7, 7, v81
	v_lshlrev_b32_e32 v6, 1, v7
	v_lshlrev_b32_e32 v20, 2, v0
	v_cndmask_b32_e32 v0, v33, v36, vcc
	v_lshlrev_b32_e32 v21, 2, v0
	v_cvt_f32_ubyte0_e32 v0, v6
	v_mul_f32_e32 v0, 0xc1135d8e, v0
	v_mul_f32_e32 v0, 0x3d800000, v0
	v_mul_f32_e32 v1, 0x3fb8aa3b, v0
	v_fma_f32 v2, v0, s35, -v1
	v_rndne_f32_e32 v3, v1
	v_fmac_f32_e32 v2, 0x32a5705f, v0
	v_sub_f32_e32 v1, v1, v3
	v_add_f32_e32 v1, v1, v2
	v_exp_f32_e32 v1, v1
	v_cvt_i32_f32_e32 v2, v3
	v_cmp_lt_i32_e32 vcc, v37, v35
	v_pk_mul_f32 v[10:11], v[10:11], v[110:111] op_sel_hi:[1,0]
	v_pk_mul_f32 v[8:9], v[8:9], v[110:111] op_sel_hi:[1,0]
	v_ldexp_f32 v1, v1, v2
	v_or_b32_e32 v2, 1, v6
	v_cvt_f32_ubyte0_e32 v2, v2
	v_mul_f32_e32 v2, 0xc1135d8e, v2
	v_cndmask_b32_e32 v3, v33, v37, vcc
	v_mul_f32_e32 v2, 0x3d800000, v2
	v_lshlrev_b32_e32 v22, 2, v3
	v_mul_f32_e32 v3, 0x3fb8aa3b, v2
	v_fma_f32 v4, v2, s35, -v3
	v_rndne_f32_e32 v5, v3
	v_fmac_f32_e32 v4, 0x32a5705f, v2
	v_sub_f32_e32 v3, v3, v5
	v_add_f32_e32 v3, v3, v4
	v_exp_f32_e32 v3, v3
	v_cvt_i32_f32_e32 v4, v5
	v_cmp_ngt_f32_e32 vcc, s36, v0
	ds_write_b128 v92, v[8:11] offset:25472
	v_ashrrev_i32_e32 v11, 3, v81
	v_cndmask_b32_e32 v1, 0, v1, vcc
	v_cmp_nlt_f32_e32 vcc, s37, v0
	v_mov_b32_e32 v5, v29
	v_lshlrev_b32_e32 v28, 3, v7
	v_cndmask_b32_e32 v0, v32, v1, vcc
	v_mul_f32_e32 v8, 0.15915494, v0
	v_ldexp_f32 v0, v3, v4
	v_cmp_ngt_f32_e32 vcc, s36, v2
	v_lshlrev_b32_e32 v4, 5, v7
	v_pk_mul_f32 v[18:19], v[18:19], v[110:111] op_sel_hi:[1,0]
	v_cndmask_b32_e32 v0, 0, v0, vcc
	v_cmp_nlt_f32_e32 vcc, s37, v2
	v_pk_mul_f32 v[16:17], v[16:17], v[110:111] op_sel_hi:[1,0]
	v_pk_mul_f32 v[14:15], v[14:15], v[110:111] op_sel_hi:[1,0]
	v_cndmask_b32_e32 v0, v32, v0, vcc
	v_mul_f32_e32 v9, 0.15915494, v0
	v_lshl_add_u64 v[0:1], s[52:53], 0, v[4:5]
	v_mad_u64_u32 v[4:5], s[72:73], v11, s34, v[4:5]
	v_pk_mul_f32 v[12:13], v[12:13], v[110:111] op_sel_hi:[1,0]
	v_lshl_add_u64 v[2:3], s[52:53], 0, v[28:29]
	v_mul_i32_i24_e32 v10, 0xffffffe8, v7
	v_add_u32_e32 v5, s8, v11
	v_lshlrev_b32_e32 v28, 1, v28
	v_lshlrev_b32_e32 v6, 1, v6
	s_mov_b32 s8, 0
	ds_write_b128 v92, v[52:55] offset:192
	ds_write_b128 v92, v[42:45] offset:17024
	ds_write_b128 v92, v[16:19] offset:25344
	ds_write_b128 v92, v[12:15] offset:25408
	s_waitcnt lgkmcnt(0)
	s_barrier

.LBB0_94:
	s_ashr_i32 s4, s65, 31
	s_lshr_b32 s4, s4, 29
	s_add_i32 s4, s65, s4
	s_ashr_i32 s71, s4, 3
	s_and_b32 s4, s4, -8
	s_or_b32 s5, s4, s33
	s_sub_i32 s72, s65, s4
	s_lshl_b32 s73, s5, 7
	s_mul_i32 s4, s5, 5
	s_mul_i32 s5, s72, 3
	s_add_i32 s4, s4, s5
	s_ashr_i32 s5, s4, 31
	s_lshr_b32 s5, s5, 30
	v_mov_b32_e32 v27, v138
	s_add_i32 s5, s4, s5
	s_and_b32 s5, s5, -4
	v_bfe_u32 v4, v27, 3, 3
	v_bitop3_b32 v16, v4, v27, 7 bitop3:0x78
	s_sub_i32 s91, s4, s5
	v_ashrrev_i32_e32 v2, 6, v27
	s_lshl_b32 s6, s91, 6
	v_lshlrev_b32_e32 v83, 3, v16
	v_lshlrev_b32_e32 v34, 12, v2
	v_lshl_or_b32 v2, v2, 5, v4
	v_or_b32_e32 v6, s6, v83
	v_add_u32_e32 v4, s73, v2
	v_ashrrev_i32_e32 v7, 31, v6
	v_mad_i64_i32 v[4:5], s[4:5], v4, s37, v[0:1]
	v_lshlrev_b64 v[12:13], 1, v[6:7]
	v_lshl_add_u64 v[6:7], v[4:5], 0, v[12:13]
	v_readfirstlane_b32 s4, v34
	v_lshl_add_u64 v[6:7], v[6:7], 0, s[12:13]
	s_mov_b32 m0, s4
	v_or_b32_e32 v17, 8, v2
	global_load_lds_dwordx4 v[6:7], off
	v_add_u32_e32 v6, s73, v17
	v_mad_i64_i32 v[6:7], s[86:87], v6, s37, v[0:1]
	v_or_b32_e32 v10, 0x400, v34
	v_lshl_add_u64 v[8:9], v[6:7], 0, v[12:13]
	v_readfirstlane_b32 s14, v10
	v_lshl_add_u64 v[8:9], v[8:9], 0, s[12:13]
	s_mov_b32 m0, s14
	v_or_b32_e32 v18, 16, v2
	global_load_lds_dwordx4 v[8:9], off
	v_add_u32_e32 v8, s73, v18
	v_mad_i64_i32 v[8:9], s[86:87], v8, s37, v[0:1]
	v_or_b32_e32 v14, 0x800, v34
	v_lshl_add_u64 v[10:11], v[8:9], 0, v[12:13]
	v_readfirstlane_b32 s87, v14
	v_lshl_add_u64 v[10:11], v[10:11], 0, s[12:13]
	s_mov_b32 m0, s87
	v_or_b32_e32 v19, 24, v2
	global_load_lds_dwordx4 v[10:11], off
	v_add_u32_e32 v10, s73, v19
	v_mad_i64_i32 v[10:11], s[88:89], v10, s37, v[0:1]
	v_or_b32_e32 v14, 0xc00, v34
	v_lshl_add_u64 v[12:13], v[10:11], 0, v[12:13]
	v_readfirstlane_b32 s90, v14
	s_lshl_b32 s85, s72, 7
	v_lshl_add_u64 v[12:13], v[12:13], 0, s[12:13]
	s_mov_b32 m0, s90
	s_ashr_i32 s7, s6, 31
	global_load_lds_dwordx4 v[12:13], off
	v_add_u32_e32 v12, s85, v2
	v_ashrrev_i32_e32 v13, 31, v12
	v_lshlrev_b64 v[12:13], 9, v[12:13]
	v_add_u32_e32 v28, 0x4000, v34
	v_lshl_add_u64 v[12:13], s[10:11], 0, v[12:13]
	s_lshl_b64 s[6:7], s[6:7], 1
	v_lshl_add_u64 v[14:15], v[12:13], 0, s[6:7]
	v_lshlrev_b32_e32 v2, 4, v16
	v_readfirstlane_b32 s92, v28
	v_lshl_add_u64 v[14:15], v[14:15], 0, v[2:3]
	s_mov_b32 m0, s92
	v_add_u32_e32 v28, 0x4400, v34
	global_load_lds_dwordx4 v[14:15], off
	v_add_u32_e32 v14, s85, v17
	v_ashrrev_i32_e32 v15, 31, v14
	v_lshlrev_b64 v[14:15], 9, v[14:15]
	v_lshl_add_u64 v[14:15], s[10:11], 0, v[14:15]
	v_lshl_add_u64 v[16:17], v[14:15], 0, s[6:7]
	v_readfirstlane_b32 s93, v28
	v_lshl_add_u64 v[16:17], v[16:17], 0, v[2:3]
	s_mov_b32 m0, s93
	s_add_i32 s91, s91, 1
	global_load_lds_dwordx4 v[16:17], off
	v_add_u32_e32 v16, s85, v18
	v_ashrrev_i32_e32 v17, 31, v16
	v_lshlrev_b64 v[16:17], 9, v[16:17]
	v_lshl_add_u64 v[28:29], s[10:11], 0, v[16:17]
	v_add_u32_e32 v18, 0x4800, v34
	v_lshl_add_u64 v[16:17], v[28:29], 0, s[6:7]
	v_readfirstlane_b32 s96, v18
	v_lshl_add_u64 v[16:17], v[16:17], 0, v[2:3]
	s_mov_b32 m0, s96
	v_add_u32_e32 v18, 0x4c00, v34
	global_load_lds_dwordx4 v[16:17], off
	v_add_u32_e32 v16, s85, v19
	v_ashrrev_i32_e32 v17, 31, v16
	v_lshlrev_b64 v[16:17], 9, v[16:17]
	v_lshl_add_u64 v[32:33], s[10:11], 0, v[16:17]
	s_cmp_lg_u32 s91, 4
	v_lshl_add_u64 v[16:17], v[32:33], 0, s[6:7]
	v_readfirstlane_b32 s97, v18
	s_cselect_b32 s98, s91, 0
	v_lshl_add_u64 v[16:17], v[16:17], 0, v[2:3]
	s_mov_b32 m0, s97
	s_lshl_b32 s88, s98, 6
	global_load_lds_dwordx4 v[16:17], off
	v_lshl_add_u64 v[16:17], v[14:15], 0, v[2:3]
	v_lshl_add_u64 v[14:15], v[28:29], 0, v[2:3]
	v_or_b32_e32 v28, s88, v83
	v_ashrrev_i32_e32 v29, 31, v28
	v_add_u32_e32 v35, 0x8000, v34
	v_lshlrev_b64 v[28:29], 1, v[28:29]
	v_lshl_add_u64 v[18:19], v[12:13], 0, v[2:3]
	v_lshl_add_u64 v[12:13], v[32:33], 0, v[2:3]
	v_lshl_add_u64 v[32:33], v[4:5], 0, v[28:29]
	v_readfirstlane_b32 s5, v35
	v_lshl_add_u64 v[32:33], v[32:33], 0, s[12:13]
	s_mov_b32 m0, s5
	v_add_u32_e32 v35, 0x8400, v34
	s_waitcnt vmcnt(0) lgkmcnt(0)
	s_barrier
	global_load_lds_dwordx4 v[32:33], off
	v_lshl_add_u64 v[32:33], v[6:7], 0, v[28:29]
	v_readfirstlane_b32 s6, v35
	v_lshl_add_u64 v[32:33], v[32:33], 0, s[12:13]
	s_mov_b32 m0, s6
	v_add_u32_e32 v35, 0x8800, v34
	global_load_lds_dwordx4 v[32:33], off
	v_lshl_add_u64 v[32:33], v[8:9], 0, v[28:29]
	v_readfirstlane_b32 s7, v35
	v_lshl_add_u64 v[32:33], v[32:33], 0, s[12:13]
	s_mov_b32 m0, s7
	v_lshl_add_u64 v[28:29], v[10:11], 0, v[28:29]
	global_load_lds_dwordx4 v[32:33], off
	v_add_u32_e32 v32, 0x8c00, v34
	s_ashr_i32 s89, s88, 31
	v_readfirstlane_b32 s85, v32
	v_add_u32_e32 v32, 0xc000, v34
	v_lshl_add_u64 v[28:29], v[28:29], 0, s[12:13]
	s_mov_b32 m0, s85
	s_lshl_b64 s[94:95], s[88:89], 1
	v_readfirstlane_b32 s86, v32
	v_add_u32_e32 v32, 0xc400, v34
	global_load_lds_dwordx4 v[28:29], off
	v_lshl_add_u64 v[28:29], v[18:19], 0, s[94:95]
	s_mov_b32 m0, s86
	v_readfirstlane_b32 s88, v32
	v_add_u32_e32 v32, 0xc800, v34
	global_load_lds_dwordx4 v[28:29], off
	v_lshl_add_u64 v[28:29], v[16:17], 0, s[94:95]
	s_mov_b32 m0, s88
	v_readfirstlane_b32 s89, v32
	v_add_u32_e32 v32, 0xcc00, v34
	global_load_lds_dwordx4 v[28:29], off
	v_lshl_add_u64 v[28:29], v[14:15], 0, s[94:95]
	s_mov_b32 m0, s89
	v_readfirstlane_b32 s91, v32
	v_bfe_u32 v31, v27, 4, 2
	global_load_lds_dwordx4 v[28:29], off
	v_lshl_add_u64 v[28:29], v[12:13], 0, s[94:95]
	s_mov_b32 m0, s91
	v_and_b32_e32 v26, 15, v27
	v_bitop3_b32 v2, v31, v27, 7 bitop3:0x78
	global_load_lds_dwordx4 v[28:29], off
	v_lshlrev_b32_e32 v29, 7, v27
	v_ashrrev_i32_e32 v25, 7, v27
	v_lshlrev_b32_e32 v2, 4, v2
	v_lshlrev_b32_e32 v28, 7, v26
	v_and_b32_e32 v29, 0x2780, v29
	v_or_b32_e32 v124, v2, v29
	v_lshl_or_b32 v28, v25, 13, v28
	ds_read_b128 v[32:35], v124 offset:16384
	v_or_b32_e32 v125, v2, v28
	ds_read_b128 v[36:39], v124 offset:18432
	ds_read_b128 v[40:43], v125
	ds_read_b128 v[44:47], v125 offset:2048
	ds_read_b128 v[52:55], v124 offset:20480
	ds_read_b128 v[60:63], v124 offset:22528
	ds_read_b128 v[84:87], v125 offset:4096
	ds_read_b128 v[88:91], v125 offset:6144
	v_and_b32_e32 v2, 7, v27
	v_bitop3_b32 v2, v31, v2, 4 bitop3:0x36
	v_lshlrev_b32_e32 v2, 4, v2
	v_or_b32_e32 v27, v2, v29
	s_waitcnt lgkmcnt(0)
	v_mfma_f32_16x16x32_bf16 v[48:51], v[32:35], v[40:43], 0
	ds_read_b128 v[104:107], v27 offset:16384
	v_or_b32_e32 v31, v2, v28
	s_add_i32 s98, s98, 1
	v_mfma_f32_16x16x32_bf16 v[56:59], v[36:39], v[40:43], 0
	s_cmp_lg_u32 s98, 4
	s_cselect_b32 s98, s98, 0
	s_lshl_b32 s94, s98, 6
	v_mfma_f32_16x16x32_bf16 v[64:67], v[52:55], v[40:43], 0
	v_or_b32_e32 v28, s94, v83
	v_ashrrev_i32_e32 v29, 31, v28
	v_lshlrev_b64 v[28:29], 1, v[28:29]
	v_mfma_f32_16x16x32_bf16 v[40:43], v[60:63], v[40:43], 0
	v_lshl_add_u64 v[80:81], v[4:5], 0, v[28:29]
	v_lshl_add_u64 v[80:81], v[80:81], 0, s[12:13]
	s_mov_b32 m0, s4
	v_mfma_f32_16x16x32_bf16 v[68:71], v[32:35], v[44:47], 0
	s_ashr_i32 s95, s94, 31
	s_lshl_b64 s[94:95], s[94:95], 1
	s_add_i32 s98, s98, 1
	v_mfma_f32_16x16x32_bf16 v[72:75], v[36:39], v[44:47], 0
	s_lshl_b32 s4, s98, 6
	s_cmp_lg_u32 s98, 4
	s_cselect_b32 s4, s4, 0
	v_mfma_f32_16x16x32_bf16 v[76:79], v[52:55], v[44:47], 0
	v_or_b32_e32 v2, s4, v83
	v_lshlrev_b32_e32 v2, 1, v2
	v_lshl_add_u64 v[4:5], v[4:5], 0, v[2:3]
	v_mfma_f32_16x16x32_bf16 v[44:47], v[60:63], v[44:47], 0
	v_lshl_add_u64 v[4:5], v[4:5], 0, s[12:13]
	v_mfma_f32_16x16x32_bf16 v[92:95], v[32:35], v[84:87], 0
	v_mfma_f32_16x16x32_bf16 v[96:99], v[36:39], v[84:87], 0
	v_mfma_f32_16x16x32_bf16 v[100:103], v[52:55], v[84:87], 0
	v_mfma_f32_16x16x32_bf16 v[84:87], v[60:63], v[84:87], 0
	v_mfma_f32_16x16x32_bf16 v[32:35], v[32:35], v[88:91], 0
	v_mfma_f32_16x16x32_bf16 v[36:39], v[36:39], v[88:91], 0
	v_mfma_f32_16x16x32_bf16 v[52:55], v[52:55], v[88:91], 0
	v_mfma_f32_16x16x32_bf16 v[60:63], v[60:63], v[88:91], 0
	ds_read_b128 v[88:91], v27 offset:18432
	ds_read_b128 v[108:111], v31
	ds_read_b128 v[112:115], v31 offset:2048
	ds_read_b128 v[116:119], v27 offset:20480
	ds_read_b128 v[120:123], v27 offset:22528
	s_waitcnt lgkmcnt(3)
	v_mfma_f32_16x16x32_bf16 v[48:51], v[104:107], v[108:111], v[48:51]
	v_mfma_f32_16x16x32_bf16 v[56:59], v[88:91], v[108:111], v[56:59]
	s_waitcnt lgkmcnt(1)
	v_mfma_f32_16x16x32_bf16 v[64:67], v[116:119], v[108:111], v[64:67]
	s_waitcnt lgkmcnt(0)
	v_mfma_f32_16x16x32_bf16 v[40:43], v[120:123], v[108:111], v[40:43]
	v_mfma_f32_16x16x32_bf16 v[68:71], v[104:107], v[112:115], v[68:71]
	v_mfma_f32_16x16x32_bf16 v[72:75], v[88:91], v[112:115], v[72:75]
	v_mfma_f32_16x16x32_bf16 v[76:79], v[116:119], v[112:115], v[76:79]
	v_mfma_f32_16x16x32_bf16 v[44:47], v[120:123], v[112:115], v[44:47]
	ds_read_b128 v[108:111], v31 offset:4096
	ds_read_b128 v[112:115], v31 offset:6144
	s_waitcnt vmcnt(0) lgkmcnt(0)
	s_barrier
	global_load_lds_dwordx4 v[80:81], off
	v_lshl_add_u64 v[80:81], v[6:7], 0, v[28:29]
	v_lshl_add_u64 v[80:81], v[80:81], 0, s[12:13]
	s_mov_b32 m0, s14
	v_mfma_f32_16x16x32_bf16 v[92:95], v[104:107], v[108:111], v[92:95]
	global_load_lds_dwordx4 v[80:81], off
	v_lshl_add_u64 v[80:81], v[8:9], 0, v[28:29]
	v_lshl_add_u64 v[80:81], v[80:81], 0, s[12:13]
	s_mov_b32 m0, s87
	v_lshl_add_u64 v[28:29], v[10:11], 0, v[28:29]
	global_load_lds_dwordx4 v[80:81], off
	v_lshl_add_u64 v[28:29], v[28:29], 0, s[12:13]
	s_mov_b32 m0, s90
	v_mfma_f32_16x16x32_bf16 v[96:99], v[88:91], v[108:111], v[96:99]
	global_load_lds_dwordx4 v[28:29], off
	v_lshl_add_u64 v[28:29], v[18:19], 0, s[94:95]
	s_mov_b32 m0, s92
	v_mfma_f32_16x16x32_bf16 v[100:103], v[116:119], v[108:111], v[100:103]
	global_load_lds_dwordx4 v[28:29], off
	v_lshl_add_u64 v[28:29], v[16:17], 0, s[94:95]
	s_mov_b32 m0, s93
	v_mfma_f32_16x16x32_bf16 v[84:87], v[120:123], v[108:111], v[84:87]
	global_load_lds_dwordx4 v[28:29], off
	v_lshl_add_u64 v[28:29], v[14:15], 0, s[94:95]
	s_mov_b32 m0, s96
	v_mfma_f32_16x16x32_bf16 v[32:35], v[104:107], v[112:115], v[32:35]
	global_load_lds_dwordx4 v[28:29], off
	v_lshl_add_u64 v[28:29], v[12:13], 0, s[94:95]
	s_mov_b32 m0, s97
	v_mfma_f32_16x16x32_bf16 v[36:39], v[88:91], v[112:115], v[36:39]
	global_load_lds_dwordx4 v[28:29], off
	ds_read_b128 v[88:91], v124 offset:49152
	v_mfma_f32_16x16x32_bf16 v[52:55], v[116:119], v[112:115], v[52:55]
	s_mov_b32 m0, s5
	s_lshl_b32 s14, s4, 1
	v_mfma_f32_16x16x32_bf16 v[60:63], v[120:123], v[112:115], v[60:63]
	ds_read_b128 v[104:107], v124 offset:51200
	ds_read_b128 v[108:111], v125 offset:32768
	ds_read_b128 v[112:115], v125 offset:34816
	ds_read_b128 v[116:119], v124 offset:53248
	ds_read_b128 v[120:123], v124 offset:55296
	s_waitcnt lgkmcnt(0)
	v_mfma_f32_16x16x32_bf16 v[48:51], v[88:91], v[108:111], v[48:51]
	v_mfma_f32_16x16x32_bf16 v[56:59], v[104:107], v[108:111], v[56:59]
	v_mfma_f32_16x16x32_bf16 v[64:67], v[116:119], v[108:111], v[64:67]
	v_mfma_f32_16x16x32_bf16 v[40:43], v[120:123], v[108:111], v[40:43]
	v_mfma_f32_16x16x32_bf16 v[68:71], v[88:91], v[112:115], v[68:71]
	v_mfma_f32_16x16x32_bf16 v[72:75], v[104:107], v[112:115], v[72:75]
	v_mfma_f32_16x16x32_bf16 v[76:79], v[116:119], v[112:115], v[76:79]
	v_mfma_f32_16x16x32_bf16 v[44:47], v[120:123], v[112:115], v[44:47]
	ds_read_b128 v[108:111], v125 offset:36864
	ds_read_b128 v[112:115], v125 offset:38912
	s_waitcnt lgkmcnt(1)
	v_mfma_f32_16x16x32_bf16 v[92:95], v[88:91], v[108:111], v[92:95]
	v_mfma_f32_16x16x32_bf16 v[96:99], v[104:107], v[108:111], v[96:99]
	v_mfma_f32_16x16x32_bf16 v[100:103], v[116:119], v[108:111], v[100:103]
	v_mfma_f32_16x16x32_bf16 v[84:87], v[120:123], v[108:111], v[84:87]
	s_waitcnt lgkmcnt(0)
	v_mfma_f32_16x16x32_bf16 v[32:35], v[88:91], v[112:115], v[32:35]
	ds_read_b128 v[88:91], v27 offset:49152
	v_mfma_f32_16x16x32_bf16 v[36:39], v[104:107], v[112:115], v[36:39]
	v_mfma_f32_16x16x32_bf16 v[52:55], v[116:119], v[112:115], v[52:55]
	v_mfma_f32_16x16x32_bf16 v[60:63], v[120:123], v[112:115], v[60:63]
	ds_read_b128 v[104:107], v27 offset:51200
	ds_read_b128 v[108:111], v31 offset:32768
	ds_read_b128 v[112:115], v31 offset:34816
	ds_read_b128 v[116:119], v27 offset:53248
	ds_read_b128 v[120:123], v27 offset:55296
	s_waitcnt lgkmcnt(3)
	v_mfma_f32_16x16x32_bf16 v[48:51], v[88:91], v[108:111], v[48:51]
	v_mfma_f32_16x16x32_bf16 v[56:59], v[104:107], v[108:111], v[56:59]
	s_waitcnt lgkmcnt(1)
	v_mfma_f32_16x16x32_bf16 v[64:67], v[116:119], v[108:111], v[64:67]
	s_waitcnt lgkmcnt(0)
	v_mfma_f32_16x16x32_bf16 v[40:43], v[120:123], v[108:111], v[40:43]
	v_mfma_f32_16x16x32_bf16 v[68:71], v[88:91], v[112:115], v[68:71]
	v_mfma_f32_16x16x32_bf16 v[72:75], v[104:107], v[112:115], v[72:75]
	v_mfma_f32_16x16x32_bf16 v[76:79], v[116:119], v[112:115], v[76:79]
	v_mfma_f32_16x16x32_bf16 v[44:47], v[120:123], v[112:115], v[44:47]
	ds_read_b128 v[108:111], v31 offset:36864
	ds_read_b128 v[112:115], v31 offset:38912
	s_waitcnt vmcnt(0) lgkmcnt(0)
	s_barrier
	global_load_lds_dwordx4 v[4:5], off
	v_lshl_add_u64 v[4:5], v[6:7], 0, v[2:3]
	v_lshl_add_u64 v[4:5], v[4:5], 0, s[12:13]
	s_mov_b32 m0, s6
	v_mfma_f32_16x16x32_bf16 v[92:95], v[88:91], v[108:111], v[92:95]
	global_load_lds_dwordx4 v[4:5], off
	v_lshl_add_u64 v[4:5], v[8:9], 0, v[2:3]
	v_lshl_add_u64 v[4:5], v[4:5], 0, s[12:13]
	s_mov_b32 m0, s7
	v_mfma_f32_16x16x32_bf16 v[96:99], v[104:107], v[108:111], v[96:99]
	global_load_lds_dwordx4 v[4:5], off
	v_lshl_add_u64 v[4:5], v[10:11], 0, v[2:3]
	v_lshl_add_u64 v[4:5], v[4:5], 0, s[12:13]
	s_mov_b32 m0, s85
	v_mfma_f32_16x16x32_bf16 v[32:35], v[88:91], v[112:115], v[32:35]
	global_load_lds_dwordx4 v[4:5], off
	v_lshl_add_u64 v[4:5], v[18:19], 0, s[14:15]
	s_mov_b32 m0, s86
	v_mfma_f32_16x16x32_bf16 v[36:39], v[104:107], v[112:115], v[36:39]
	global_load_lds_dwordx4 v[4:5], off
	v_lshl_add_u64 v[4:5], v[16:17], 0, s[14:15]
	s_mov_b32 m0, s88
	v_mfma_f32_16x16x32_bf16 v[8:11], v[120:123], v[112:115], v[60:63]
	global_load_lds_dwordx4 v[4:5], off
	v_lshl_add_u64 v[4:5], v[14:15], 0, s[14:15]
	s_mov_b32 m0, s89
	v_mfma_f32_16x16x32_bf16 v[100:103], v[116:119], v[108:111], v[100:103]
	global_load_lds_dwordx4 v[4:5], off
	v_lshl_add_u64 v[4:5], v[12:13], 0, s[14:15]
	s_mov_b32 m0, s91
	v_mfma_f32_16x16x32_bf16 v[84:87], v[120:123], v[108:111], v[84:87]
	global_load_lds_dwordx4 v[4:5], off
	ds_read_b128 v[4:7], v124 offset:16384
	ds_read_b128 v[12:15], v124 offset:18432
	ds_read_b128 v[16:19], v125
	ds_read_b128 v[60:63], v125 offset:2048
	ds_read_b128 v[88:91], v124 offset:20480
	ds_read_b128 v[104:107], v124 offset:22528
	s_waitcnt lgkmcnt(0)
	v_mfma_f32_16x16x32_bf16 v[48:51], v[4:7], v[16:19], v[48:51]
	v_lshl_add_u32 v2, v25, 6, s73
	v_or_b32_e32 v26, v2, v26
	v_mfma_f32_16x16x32_bf16 v[56:59], v[12:15], v[16:19], v[56:59]
	v_mfma_f32_16x16x32_bf16 v[64:67], v[88:91], v[16:19], v[64:67]
	v_mfma_f32_16x16x32_bf16 v[16:19], v[104:107], v[16:19], v[40:43]
	v_mfma_f32_16x16x32_bf16 v[40:43], v[4:7], v[60:63], v[68:71]
	v_mfma_f32_16x16x32_bf16 v[68:71], v[12:15], v[60:63], v[72:75]
	v_mfma_f32_16x16x32_bf16 v[72:75], v[88:91], v[60:63], v[76:79]
	v_mfma_f32_16x16x32_bf16 v[44:47], v[104:107], v[60:63], v[44:47]
	ds_read_b128 v[60:63], v125 offset:4096
	s_nop 0
	ds_read_b128 v[76:79], v125 offset:6144
	v_mfma_f32_16x16x32_bf16 v[52:55], v[116:119], v[112:115], v[52:55]
	s_waitcnt lgkmcnt(1)
	v_mfma_f32_16x16x32_bf16 v[92:95], v[4:7], v[60:63], v[92:95]
	v_mfma_f32_16x16x32_bf16 v[96:99], v[12:15], v[60:63], v[96:99]
	v_mfma_f32_16x16x32_bf16 v[100:103], v[88:91], v[60:63], v[100:103]
	v_mfma_f32_16x16x32_bf16 v[60:63], v[104:107], v[60:63], v[84:87]
	s_waitcnt lgkmcnt(0)
	v_mfma_f32_16x16x32_bf16 v[4:7], v[4:7], v[76:79], v[32:35]
	v_mfma_f32_16x16x32_bf16 v[12:15], v[12:15], v[76:79], v[36:39]
	v_mfma_f32_16x16x32_bf16 v[32:35], v[88:91], v[76:79], v[52:55]
	s_nop 1
	ds_read_b128 v[36:39], v27 offset:16384
	v_mfma_f32_16x16x32_bf16 v[8:11], v[104:107], v[76:79], v[8:11]
	ds_read_b128 v[52:55], v27 offset:18432
	ds_read_b128 v[76:79], v31
	ds_read_b128 v[84:87], v31 offset:2048
	ds_read_b128 v[88:91], v27 offset:20480
	ds_read_b128 v[104:107], v27 offset:22528
	s_waitcnt lgkmcnt(3)
	v_mfma_f32_16x16x32_bf16 v[48:51], v[36:39], v[76:79], v[48:51]
	v_mfma_f32_16x16x32_bf16 v[56:59], v[52:55], v[76:79], v[56:59]
	s_waitcnt lgkmcnt(1)
	v_mfma_f32_16x16x32_bf16 v[64:67], v[88:91], v[76:79], v[64:67]
	s_waitcnt lgkmcnt(0)
	v_mfma_f32_16x16x32_bf16 v[16:19], v[104:107], v[76:79], v[16:19]
	v_mfma_f32_16x16x32_bf16 v[40:43], v[36:39], v[84:87], v[40:43]
	v_mfma_f32_16x16x32_bf16 v[68:71], v[52:55], v[84:87], v[68:71]
	v_mfma_f32_16x16x32_bf16 v[72:75], v[88:91], v[84:87], v[72:75]
	v_mfma_f32_16x16x32_bf16 v[44:47], v[104:107], v[84:87], v[44:47]
	ds_read_b128 v[76:79], v31 offset:4096
	ds_read_b128 v[84:87], v31 offset:6144
	s_waitcnt vmcnt(0) lgkmcnt(0)
	s_barrier
	v_mfma_f32_16x16x32_bf16 v[92:95], v[36:39], v[76:79], v[92:95]
	v_mfma_f32_16x16x32_bf16 v[96:99], v[52:55], v[76:79], v[96:99]
	v_mfma_f32_16x16x32_bf16 v[100:103], v[88:91], v[76:79], v[100:103]
	v_mfma_f32_16x16x32_bf16 v[60:63], v[104:107], v[76:79], v[60:63]
	ds_read_b128 v[76:79], v124 offset:51200
	v_mfma_f32_16x16x32_bf16 v[4:7], v[36:39], v[84:87], v[4:7]
	ds_read_b128 v[36:39], v124 offset:49152
	v_mfma_f32_16x16x32_bf16 v[12:15], v[52:55], v[84:87], v[12:15]
	ds_read_b128 v[52:55], v125 offset:32768
	v_mfma_f32_16x16x32_bf16 v[32:35], v[88:91], v[84:87], v[32:35]
	ds_read_b128 v[88:91], v124 offset:55296
	v_mfma_f32_16x16x32_bf16 v[8:11], v[104:107], v[84:87], v[8:11]
	ds_read_b128 v[84:87], v124 offset:53248
	ds_read_b128 v[104:107], v31 offset:38912
	s_waitcnt lgkmcnt(3)
	v_mfma_f32_16x16x32_bf16 v[48:51], v[36:39], v[52:55], v[48:51]
	v_mfma_f32_16x16x32_bf16 v[56:59], v[76:79], v[52:55], v[56:59]
	s_waitcnt lgkmcnt(1)
	v_mfma_f32_16x16x32_bf16 v[64:67], v[84:87], v[52:55], v[64:67]
	v_mfma_f32_16x16x32_bf16 v[16:19], v[88:91], v[52:55], v[16:19]
	ds_read_b128 v[52:55], v125 offset:34816
	s_waitcnt lgkmcnt(0)
	v_mfma_f32_16x16x32_bf16 v[40:43], v[36:39], v[52:55], v[40:43]
	v_mfma_f32_16x16x32_bf16 v[68:71], v[76:79], v[52:55], v[68:71]
	v_mfma_f32_16x16x32_bf16 v[72:75], v[84:87], v[52:55], v[72:75]
	v_mfma_f32_16x16x32_bf16 v[44:47], v[88:91], v[52:55], v[44:47]
	ds_read_b128 v[52:55], v125 offset:36864
	s_waitcnt lgkmcnt(0)
	v_mfma_f32_16x16x32_bf16 v[92:95], v[36:39], v[52:55], v[92:95]
	v_mfma_f32_16x16x32_bf16 v[96:99], v[76:79], v[52:55], v[96:99]
	v_mfma_f32_16x16x32_bf16 v[100:103], v[84:87], v[52:55], v[100:103]
	v_mfma_f32_16x16x32_bf16 v[52:55], v[88:91], v[52:55], v[60:63]
	s_nop 2
	ds_read_b128 v[60:63], v125 offset:38912
	s_waitcnt lgkmcnt(0)
	v_mfma_f32_16x16x32_bf16 v[4:7], v[36:39], v[60:63], v[4:7]
	ds_read_b128 v[36:39], v27 offset:49152
	v_mfma_f32_16x16x32_bf16 v[12:15], v[76:79], v[60:63], v[12:15]
	ds_read_b128 v[76:79], v27 offset:51200
	v_mfma_f32_16x16x32_bf16 v[32:35], v[84:87], v[60:63], v[32:35]
	ds_read_b128 v[84:87], v27 offset:53248
	v_mfma_f32_16x16x32_bf16 v[8:11], v[88:91], v[60:63], v[8:11]
	ds_read_b128 v[88:91], v27 offset:55296
	ds_read_b128 v[60:63], v31 offset:32768
	v_ashrrev_i32_e32 v27, 31, v26
	s_waitcnt lgkmcnt(0)
	v_mfma_f32_16x16x32_bf16 v[48:51], v[36:39], v[60:63], v[48:51]
	v_lshl_add_u64 v[80:81], v[26:27], 2, s[8:9]
	v_mfma_f32_16x16x32_bf16 v[56:59], v[76:79], v[60:63], v[56:59]
	v_mfma_f32_16x16x32_bf16 v[64:67], v[84:87], v[60:63], v[64:67]
	v_mfma_f32_16x16x32_bf16 v[16:19], v[88:91], v[60:63], v[16:19]
	ds_read_b128 v[60:63], v31 offset:34816
	s_waitcnt lgkmcnt(0)
	v_mfma_f32_16x16x32_bf16 v[40:43], v[36:39], v[60:63], v[40:43]
	v_mfma_f32_16x16x32_bf16 v[68:71], v[76:79], v[60:63], v[68:71]
	v_mfma_f32_16x16x32_bf16 v[72:75], v[84:87], v[60:63], v[72:75]
	v_mfma_f32_16x16x32_bf16 v[44:47], v[88:91], v[60:63], v[44:47]
	ds_read_b128 v[60:63], v31 offset:36864
	s_waitcnt lgkmcnt(0)
	s_barrier
	global_load_dword v2, v[80:81], off
	global_load_dword v25, v[80:81], off offset:64
	global_load_dword v31, v[80:81], off offset:128
	v_mfma_f32_16x16x32_bf16 v[92:95], v[36:39], v[60:63], v[92:95]
	v_mfma_f32_16x16x32_bf16 v[96:99], v[76:79], v[60:63], v[96:99]
	v_mfma_f32_16x16x32_bf16 v[26:29], v[84:87], v[60:63], v[100:103]
	v_mfma_f32_16x16x32_bf16 v[52:55], v[88:91], v[60:63], v[52:55]
	global_load_dword v60, v[80:81], off offset:192
	s_waitcnt vmcnt(3)
	v_fmamk_f32 v2, v2, 0x3b800000, v23
	v_mul_f32_e32 v61, 0x4b800000, v2
	v_cmp_gt_f32_e32 vcc, s38, v2
	v_mfma_f32_16x16x32_bf16 v[4:7], v[36:39], v[104:107], v[4:7]
	s_nop 0
	v_cndmask_b32_e32 v2, v2, v61, vcc
	v_rsq_f32_e32 v2, v2
	v_mfma_f32_16x16x32_bf16 v[36:39], v[76:79], v[104:107], v[12:15]
	s_waitcnt vmcnt(2)
	s_nop 1
	v_fmamk_f32 v12, v25, 0x3b800000, v23
	v_mul_f32_e32 v13, 0x4b800000, v12
	v_cmp_gt_f32_e64 s[4:5], s38, v12
	s_waitcnt vmcnt(1)
	v_fmamk_f32 v14, v31, 0x3b800000, v23
	v_mul_f32_e32 v15, 0x4b800000, v14
	v_cndmask_b32_e64 v12, v12, v13, s[4:5]
	v_mul_f32_e32 v13, 0x45800000, v2
	v_cndmask_b32_e32 v2, v2, v13, vcc
	v_cmp_gt_f32_e32 vcc, s38, v14
	v_rsq_f32_e32 v12, v12
	v_mfma_f32_16x16x32_bf16 v[32:35], v[84:87], v[104:107], v[32:35]
	v_cndmask_b32_e32 v14, v14, v15, vcc
	s_waitcnt vmcnt(0)
	v_fmamk_f32 v15, v60, 0x3b800000, v23
	v_mul_f32_e32 v25, 0x4b800000, v15
	v_cmp_gt_f32_e64 s[6:7], s38, v15
	v_rsq_f32_e32 v14, v14
	v_mul_f32_e32 v13, 0x45800000, v12
	v_cndmask_b32_e64 v15, v15, v25, s[6:7]
	v_rsq_f32_e32 v15, v15
	v_cndmask_b32_e64 v12, v12, v13, s[4:5]
	v_mul_f32_e32 v13, 0x45800000, v14
	v_cndmask_b32_e32 v60, v14, v13, vcc
	v_mul_f32_e32 v13, 0x45800000, v15
	v_mov_b32_e32 v14, v138
	v_cndmask_b32_e64 v62, v15, v13, s[6:7]
	v_mfma_f32_16x16x32_bf16 v[8:11], v[88:91], v[104:107], v[8:11]
	v_and_b32_e32 v15, 15, v14
	v_lshrrev_b32_e32 v25, 1, v14
	v_and_b32_e32 v13, 64, v14
	v_and_or_b32 v15, v25, s39, v15
	v_and_b32_e32 v25, 48, v14
	v_lshl_or_b32 v76, v13, 2, v25
	v_mad_u64_u32 v[76:77], s[4:5], v15, s50, v[76:77]
	v_pk_mul_f32 v[18:19], v[18:19], v[2:3] op_sel_hi:[1,0]
	v_pk_mul_f32 v[16:17], v[16:17], v[2:3] op_sel_hi:[1,0]
	v_pk_mul_f32 v[6:7], v[6:7], v[62:63] op_sel_hi:[1,0]
	v_pk_mul_f32 v[4:5], v[4:5], v[62:63] op_sel_hi:[1,0]
	ds_write_b128 v76, v[16:19] offset:192
	v_pk_mul_f32 v[18:19], v[42:43], v[12:13] op_sel_hi:[1,0]
	v_pk_mul_f32 v[16:17], v[40:41], v[12:13] op_sel_hi:[1,0]
	ds_write_b128 v76, v[4:7] offset:25344
	v_pk_mul_f32 v[6:7], v[38:39], v[62:63] op_sel_hi:[1,0]
	v_pk_mul_f32 v[4:5], v[36:37], v[62:63] op_sel_hi:[1,0]
	ds_write_b128 v76, v[16:19] offset:8448
	v_pk_mul_f32 v[18:19], v[70:71], v[12:13] op_sel_hi:[1,0]
	v_pk_mul_f32 v[16:17], v[68:69], v[12:13] op_sel_hi:[1,0]
	ds_write_b128 v76, v[4:7] offset:25408
	v_pk_mul_f32 v[6:7], v[34:35], v[62:63] op_sel_hi:[1,0]
	v_pk_mul_f32 v[4:5], v[32:33], v[62:63] op_sel_hi:[1,0]
	v_pk_mul_f32 v[50:51], v[50:51], v[2:3] op_sel_hi:[1,0]
	v_pk_mul_f32 v[48:49], v[48:49], v[2:3] op_sel_hi:[1,0]
	ds_write_b128 v76, v[16:19] offset:8512
	v_pk_mul_f32 v[18:19], v[74:75], v[12:13] op_sel_hi:[1,0]
	v_pk_mul_f32 v[16:17], v[72:73], v[12:13] op_sel_hi:[1,0]
	ds_write_b128 v76, v[4:7] offset:25472
	v_pk_mul_f32 v[4:5], v[8:9], v[62:63] op_sel_hi:[1,0]
	v_and_b32_e32 v8, 7, v14
	ds_write_b128 v76, v[48:51]
	v_pk_mul_f32 v[50:51], v[58:59], v[2:3] op_sel_hi:[1,0]
	v_pk_mul_f32 v[48:49], v[56:57], v[2:3] op_sel_hi:[1,0]
	ds_write_b128 v76, v[16:19] offset:8576
	v_pk_mul_f32 v[18:19], v[46:47], v[12:13] op_sel_hi:[1,0]
	v_pk_mul_f32 v[16:17], v[44:45], v[12:13] op_sel_hi:[1,0]
	v_lshlrev_b32_e32 v12, 1, v8
	ds_write_b128 v76, v[48:51] offset:64
	v_pk_mul_f32 v[50:51], v[66:67], v[2:3] op_sel_hi:[1,0]
	v_pk_mul_f32 v[48:49], v[64:65], v[2:3] op_sel_hi:[1,0]
	v_cvt_f32_ubyte0_e32 v2, v12
	v_pk_mul_f32 v[6:7], v[10:11], v[62:63] op_sel_hi:[1,0]
	v_mul_f32_e32 v2, 0xc1135d8e, v2
	ds_write_b128 v76, v[4:7] offset:25536
	v_mul_f32_e32 v4, 0x3d800000, v2
	v_mul_f32_e32 v2, 0x3fb8aa3b, v4
	v_fma_f32 v5, v4, s51, -v2
	v_rndne_f32_e32 v6, v2
	v_fmac_f32_e32 v5, 0x32a5705f, v4
	v_sub_f32_e32 v2, v2, v6
	v_add_f32_e32 v2, v2, v5
	v_exp_f32_e32 v5, v2
	v_cvt_i32_f32_e32 v6, v6
	v_cmp_ngt_f32_e32 vcc, s52, v4
	ds_write_b128 v76, v[16:19] offset:8640
	v_pk_mul_f32 v[18:19], v[94:95], v[60:61] op_sel_hi:[1,0]
	v_ldexp_f32 v5, v5, v6
	v_or_b32_e32 v6, 1, v12
	v_cvt_f32_ubyte0_e32 v6, v6
	v_mul_f32_e32 v6, 0xc1135d8e, v6
	v_mul_f32_e32 v6, 0x3d800000, v6
	v_mul_f32_e32 v7, 0x3fb8aa3b, v6
	v_fma_f32 v9, v6, s51, -v7
	v_rndne_f32_e32 v10, v7
	v_fmac_f32_e32 v9, 0x32a5705f, v6
	v_sub_f32_e32 v7, v7, v10
	v_add_f32_e32 v7, v7, v9
	v_exp_f32_e32 v7, v7
	v_cvt_i32_f32_e32 v9, v10
	v_cndmask_b32_e32 v5, 0, v5, vcc
	v_cmp_nlt_f32_e32 vcc, s53, v4
	v_pk_mul_f32 v[16:17], v[92:93], v[60:61] op_sel_hi:[1,0]
	ds_write_b128 v76, v[16:19] offset:16896
	v_cndmask_b32_e32 v4, v24, v5, vcc
	v_pk_mul_f32 v[18:19], v[98:99], v[60:61] op_sel_hi:[1,0]
	v_pk_mul_f32 v[16:17], v[96:97], v[60:61] op_sel_hi:[1,0]
	s_mul_i32 s4, s72, 0x60
	v_mul_f32_e32 v15, 0.15915494, v4
	v_ldexp_f32 v4, v7, v9
	v_cmp_ngt_f32_e32 vcc, s52, v6
	ds_write_b128 v76, v[16:19] offset:16960
	v_pk_mul_f32 v[18:19], v[28:29], v[60:61] op_sel_hi:[1,0]
	v_pk_mul_f32 v[16:17], v[26:27], v[60:61] op_sel_hi:[1,0]
	s_ashr_i32 s5, s4, 31
	v_cndmask_b32_e32 v4, 0, v4, vcc
	v_cmp_nlt_f32_e32 vcc, s53, v6
	ds_write_b128 v76, v[16:19] offset:17024
	v_pk_mul_f32 v[18:19], v[54:55], v[60:61] op_sel_hi:[1,0]
	v_pk_mul_f32 v[16:17], v[52:53], v[60:61] op_sel_hi:[1,0]
	v_ashrrev_i32_e32 v13, 3, v14
	v_cndmask_b32_e32 v4, v24, v4, vcc
	v_lshlrev_b32_e32 v10, 5, v8
	v_mov_b32_e32 v11, v3
	s_lshl_b64 s[4:5], s[4:5], 1
	ds_write_b128 v76, v[16:19] offset:17088
	v_mul_f32_e32 v16, 0.15915494, v4
	v_lshl_add_u64 v[4:5], s[54:55], 0, v[10:11]
	s_add_u32 s4, s31, s4
	v_mad_u64_u32 v[10:11], s[6:7], v13, s50, v[10:11]
	s_addc_u32 s5, s34, s5
	s_lshl_b32 s6, s71, 10
	v_lshlrev_b32_e32 v2, 3, v8
	v_lshlrev_b32_e32 v8, 2, v8
	v_mov_b32_e32 v9, v3
	s_or_b32 s6, s6, s30
	v_lshl_add_u64 v[6:7], s[54:55], 0, v[2:3]
	v_lshl_add_u64 v[8:9], s[80:81], 0, v[8:9]
	v_add_u32_e32 v11, s6, v13
	v_lshlrev_b32_e32 v2, 1, v2
	v_lshlrev_b32_e32 v12, 1, v12
	s_mov_b32 s6, 0
	ds_write_b128 v76, v[48:51] offset:128
	s_waitcnt lgkmcnt(0)
	s_barrier

.LBB0_213:
	s_mul_hi_i32 s4, s40, 0x66666667
	s_lshr_b32 s5, s4, 31
	s_ashr_i32 s4, s4, 3
	s_add_i32 s4, s4, s5
	s_lshl_b32 s5, s4, 3
	s_mul_i32 s4, s4, 20
	s_or_b32 s5, s5, s33
	s_sub_i32 s4, s40, s4
	s_lshl_b32 s41, s5, 7
	s_lshl_b32 s6, s4, 7
	s_mul_i32 s5, s5, 5
	s_mul_i32 s4, s4, 3
	s_add_i32 s4, s5, s4
	s_ashr_i32 s5, s4, 31
	s_lshr_b32 s5, s5, 30
	v_mov_b32_e32 v18, v138
	s_add_i32 s5, s4, s5
	s_and_b32 s5, s5, -4
	v_ashrrev_i32_e32 v0, 6, v18
	v_bfe_u32 v1, v18, 3, 3
	v_bitop3_b32 v8, v1, v18, 7 bitop3:0x78
	s_sub_i32 s7, s4, s5
	v_lshl_or_b32 v12, v0, 5, v1
	v_and_b32_e32 v20, 1, v0
	s_lshl_b32 s8, s7, 6
	v_lshlrev_b32_e32 v26, 12, v0
	v_add_u32_e32 v0, s41, v12
	v_lshlrev_b32_e32 v112, 3, v8
	v_or_b32_e32 v2, s8, v112
	v_ashrrev_i32_e32 v1, 31, v0
	v_lshlrev_b64 v[0:1], 9, v[0:1]
	v_ashrrev_i32_e32 v3, 31, v2
	v_lshl_add_u64 v[0:1], s[14:15], 0, v[0:1]
	v_lshlrev_b64 v[10:11], 1, v[2:3]
	v_readfirstlane_b32 s4, v26
	v_lshl_add_u64 v[2:3], v[0:1], 0, v[10:11]
	s_mov_b32 m0, s4
	v_or_b32_e32 v14, 8, v12
	global_load_lds_dwordx4 v[2:3], off
	v_add_u32_e32 v2, s41, v14
	v_ashrrev_i32_e32 v3, 31, v2
	v_lshlrev_b64 v[2:3], 9, v[2:3]
	v_or_b32_e32 v6, 0x400, v26
	v_lshl_add_u64 v[2:3], s[14:15], 0, v[2:3]
	v_readfirstlane_b32 s5, v6
	v_lshl_add_u64 v[4:5], v[2:3], 0, v[10:11]
	s_mov_b32 m0, s5
	v_or_b32_e32 v16, 16, v12
	global_load_lds_dwordx4 v[4:5], off
	v_add_u32_e32 v4, s41, v16
	v_ashrrev_i32_e32 v5, 31, v4
	v_lshlrev_b64 v[4:5], 9, v[4:5]
	v_or_b32_e32 v13, 0x800, v26
	v_lshl_add_u64 v[4:5], s[14:15], 0, v[4:5]
	v_readfirstlane_b32 s10, v13
	v_lshl_add_u64 v[6:7], v[4:5], 0, v[10:11]
	s_mov_b32 m0, s10
	v_or_b32_e32 v17, 24, v12
	global_load_lds_dwordx4 v[6:7], off
	v_add_u32_e32 v6, s41, v17
	v_ashrrev_i32_e32 v7, 31, v6
	v_lshlrev_b64 v[6:7], 9, v[6:7]
	v_or_b32_e32 v13, 0xc00, v26
	v_lshl_add_u64 v[6:7], s[14:15], 0, v[6:7]
	v_readfirstlane_b32 s28, v13
	v_lshl_add_u64 v[10:11], v[6:7], 0, v[10:11]
	s_mov_b32 m0, s28
	s_ashr_i32 s9, s8, 31
	global_load_lds_dwordx4 v[10:11], off
	v_add_u32_e32 v10, s6, v12
	v_ashrrev_i32_e32 v11, 31, v10
	v_lshlrev_b64 v[10:11], 9, v[10:11]
	v_add_u32_e32 v15, 0x4000, v26
	v_lshl_add_u64 v[10:11], s[26:27], 0, v[10:11]
	s_lshl_b64 s[8:9], s[8:9], 1
	v_lshl_add_u64 v[12:13], v[10:11], 0, s[8:9]
	v_lshlrev_b32_e32 v8, 4, v8
	v_readfirstlane_b32 s36, v15
	v_lshl_add_u64 v[12:13], v[12:13], 0, v[8:9]
	s_mov_b32 m0, s36
	v_add_u32_e32 v22, 0x4400, v26
	global_load_lds_dwordx4 v[12:13], off
	v_add_u32_e32 v12, s6, v14
	v_ashrrev_i32_e32 v13, 31, v12
	v_lshlrev_b64 v[12:13], 9, v[12:13]
	v_lshl_add_u64 v[12:13], s[26:27], 0, v[12:13]
	v_lshl_add_u64 v[14:15], v[12:13], 0, s[8:9]
	v_readfirstlane_b32 s37, v22
	v_lshl_add_u64 v[14:15], v[14:15], 0, v[8:9]
	s_mov_b32 m0, s37
	s_add_i32 s7, s7, 1
	global_load_lds_dwordx4 v[14:15], off
	v_add_u32_e32 v14, s6, v16
	v_ashrrev_i32_e32 v15, 31, v14
	v_lshlrev_b64 v[14:15], 9, v[14:15]
	v_lshl_add_u64 v[22:23], s[26:27], 0, v[14:15]
	v_add_u32_e32 v16, 0x4800, v26
	v_lshl_add_u64 v[14:15], v[22:23], 0, s[8:9]
	v_readfirstlane_b32 s52, v16
	v_lshl_add_u64 v[14:15], v[14:15], 0, v[8:9]
	s_mov_b32 m0, s52
	v_add_u32_e32 v16, 0x4c00, v26
	global_load_lds_dwordx4 v[14:15], off
	v_add_u32_e32 v14, s6, v17
	v_ashrrev_i32_e32 v15, 31, v14
	v_lshlrev_b64 v[14:15], 9, v[14:15]
	v_lshl_add_u64 v[24:25], s[26:27], 0, v[14:15]
	s_cmp_lg_u32 s7, 4
	v_lshl_add_u64 v[14:15], v[24:25], 0, s[8:9]
	v_readfirstlane_b32 s53, v16
	s_cselect_b32 s54, s7, 0
	v_lshl_add_u64 v[14:15], v[14:15], 0, v[8:9]
	s_mov_b32 m0, s53
	s_lshl_b32 s12, s54, 6
	global_load_lds_dwordx4 v[14:15], off
	v_lshl_add_u64 v[14:15], v[12:13], 0, v[8:9]
	v_lshl_add_u64 v[12:13], v[22:23], 0, v[8:9]
	v_or_b32_e32 v22, s12, v112
	v_add_u32_e32 v27, 0x8000, v26
	v_ashrrev_i32_e32 v23, 31, v22
	v_lshlrev_b64 v[22:23], 1, v[22:23]
	v_readfirstlane_b32 s7, v27
	v_add_u32_e32 v27, 0x8400, v26
	v_lshl_add_u64 v[16:17], v[10:11], 0, v[8:9]
	v_lshl_add_u64 v[10:11], v[24:25], 0, v[8:9]
	v_lshl_add_u64 v[24:25], v[0:1], 0, v[22:23]
	s_mov_b32 m0, s7
	v_readfirstlane_b32 s8, v27
	v_add_u32_e32 v27, 0x8800, v26
	s_waitcnt vmcnt(0) lgkmcnt(0)
	s_barrier
	global_load_lds_dwordx4 v[24:25], off
	v_lshl_add_u64 v[24:25], v[2:3], 0, v[22:23]
	s_mov_b32 m0, s8
	v_readfirstlane_b32 s9, v27
	global_load_lds_dwordx4 v[24:25], off
	v_lshl_add_u64 v[24:25], v[4:5], 0, v[22:23]
	s_mov_b32 m0, s9
	s_ashr_i32 s13, s12, 31
	global_load_lds_dwordx4 v[24:25], off
	v_add_u32_e32 v24, 0x8c00, v26
	v_lshl_add_u64 v[22:23], v[6:7], 0, v[22:23]
	v_readfirstlane_b32 s11, v24
	v_add_u32_e32 v24, 0xc000, v26
	s_mov_b32 m0, s11
	s_lshl_b64 s[50:51], s[12:13], 1
	v_readfirstlane_b32 s12, v24
	v_add_u32_e32 v24, 0xc400, v26
	global_load_lds_dwordx4 v[22:23], off
	v_lshl_add_u64 v[22:23], v[16:17], 0, s[50:51]
	s_mov_b32 m0, s12
	v_readfirstlane_b32 s13, v24
	v_add_u32_e32 v24, 0xc800, v26
	v_bfe_u32 v83, v18, 4, 2
	v_and_b32_e32 v21, 15, v18
	global_load_lds_dwordx4 v[22:23], off
	v_lshl_add_u64 v[22:23], v[14:15], 0, s[50:51]
	s_mov_b32 m0, s13
	v_readfirstlane_b32 s34, v24
	v_add_u32_e32 v24, 0xcc00, v26
	v_bitop3_b32 v8, v83, v18, 7 bitop3:0x78
	global_load_lds_dwordx4 v[22:23], off
	v_lshl_add_u64 v[22:23], v[12:13], 0, s[50:51]
	s_mov_b32 m0, s34
	v_readfirstlane_b32 s35, v24
	v_lshlrev_b32_e32 v26, 7, v21
	v_ashrrev_i32_e32 v19, 7, v18
	global_load_lds_dwordx4 v[22:23], off
	v_lshl_add_u64 v[22:23], v[10:11], 0, s[50:51]
	s_mov_b32 m0, s35
	v_lshlrev_b32_e32 v8, 4, v8
	v_lshl_or_b32 v92, v20, 13, v26
	global_load_lds_dwordx4 v[22:23], off
	v_or_b32_e32 v113, v8, v92
	v_lshl_or_b32 v96, v19, 13, v26
	ds_read_b128 v[22:25], v113 offset:16384
	v_or_b32_e32 v114, v8, v96
	ds_read_b128 v[26:29], v113 offset:18432
	ds_read_b128 v[30:33], v114
	ds_read_b128 v[34:37], v114 offset:2048
	ds_read_b128 v[42:45], v113 offset:20480
	ds_read_b128 v[50:53], v113 offset:22528
	ds_read_b128 v[70:73], v114 offset:4096
	ds_read_b128 v[74:77], v114 offset:6144
	v_and_b32_e32 v8, 7, v18
	v_bitop3_b32 v8, v83, v8, 4 bitop3:0x36
	v_lshlrev_b32_e32 v8, 4, v8
	v_or_b32_e32 v83, v8, v92
	s_waitcnt lgkmcnt(0)
	v_mfma_f32_16x16x32_bf16 v[38:41], v[22:25], v[30:33], 0
	ds_read_b128 v[92:95], v83 offset:16384
	v_or_b32_e32 v115, v8, v96
	s_add_i32 s54, s54, 1
	v_mfma_f32_16x16x32_bf16 v[46:49], v[26:29], v[30:33], 0
	s_cmp_lg_u32 s54, 4
	s_cselect_b32 s54, s54, 0
	s_lshl_b32 s50, s54, 6
	v_mfma_f32_16x16x32_bf16 v[54:57], v[42:45], v[30:33], 0
	s_mov_b32 m0, s4
	s_ashr_i32 s51, s50, 31
	s_add_i32 s54, s54, 1
	v_mfma_f32_16x16x32_bf16 v[30:33], v[50:53], v[30:33], 0
	v_lshl_or_b32 v19, v19, 6, v21
	v_mfma_f32_16x16x32_bf16 v[58:61], v[22:25], v[34:37], 0
	v_mfma_f32_16x16x32_bf16 v[62:65], v[26:29], v[34:37], 0
	v_mfma_f32_16x16x32_bf16 v[66:69], v[42:45], v[34:37], 0
	v_mfma_f32_16x16x32_bf16 v[34:37], v[50:53], v[34:37], 0
	v_mfma_f32_16x16x32_bf16 v[78:81], v[22:25], v[70:73], 0
	v_mfma_f32_16x16x32_bf16 v[84:87], v[26:29], v[70:73], 0
	v_mfma_f32_16x16x32_bf16 v[88:91], v[42:45], v[70:73], 0
	v_mfma_f32_16x16x32_bf16 v[70:73], v[50:53], v[70:73], 0
	v_mfma_f32_16x16x32_bf16 v[22:25], v[22:25], v[74:77], 0
	v_mfma_f32_16x16x32_bf16 v[26:29], v[26:29], v[74:77], 0
	v_mfma_f32_16x16x32_bf16 v[42:45], v[42:45], v[74:77], 0
	v_mfma_f32_16x16x32_bf16 v[50:53], v[50:53], v[74:77], 0
	ds_read_b128 v[74:77], v83 offset:18432
	ds_read_b128 v[96:99], v115
	ds_read_b128 v[100:103], v115 offset:2048
	ds_read_b128 v[104:107], v83 offset:20480
	ds_read_b128 v[108:111], v83 offset:22528
	s_waitcnt lgkmcnt(3)
	v_mfma_f32_16x16x32_bf16 v[38:41], v[92:95], v[96:99], v[38:41]
	v_mfma_f32_16x16x32_bf16 v[46:49], v[74:77], v[96:99], v[46:49]
	s_waitcnt lgkmcnt(1)
	v_mfma_f32_16x16x32_bf16 v[54:57], v[104:107], v[96:99], v[54:57]
	s_waitcnt lgkmcnt(0)
	v_mfma_f32_16x16x32_bf16 v[30:33], v[108:111], v[96:99], v[30:33]
	v_mfma_f32_16x16x32_bf16 v[58:61], v[92:95], v[100:103], v[58:61]
	v_mfma_f32_16x16x32_bf16 v[62:65], v[74:77], v[100:103], v[62:65]
	v_mfma_f32_16x16x32_bf16 v[66:69], v[104:107], v[100:103], v[66:69]
	v_mfma_f32_16x16x32_bf16 v[34:37], v[108:111], v[100:103], v[34:37]
	ds_read_b128 v[96:99], v115 offset:4096
	ds_read_b128 v[100:103], v115 offset:6144
	s_waitcnt vmcnt(0) lgkmcnt(0)
	s_barrier
	v_mfma_f32_16x16x32_bf16 v[84:87], v[74:77], v[96:99], v[84:87]
	v_mfma_f32_16x16x32_bf16 v[26:29], v[74:77], v[100:103], v[26:29]
	v_or_b32_e32 v74, s50, v112
	v_ashrrev_i32_e32 v75, 31, v74
	v_lshlrev_b64 v[74:75], 1, v[74:75]
	v_lshl_add_u64 v[76:77], v[0:1], 0, v[74:75]
	global_load_lds_dwordx4 v[76:77], off
	v_lshl_add_u64 v[76:77], v[2:3], 0, v[74:75]
	s_mov_b32 m0, s5
	s_lshl_b64 s[4:5], s[50:51], 1
	global_load_lds_dwordx4 v[76:77], off
	v_lshl_add_u64 v[76:77], v[4:5], 0, v[74:75]
	s_mov_b32 m0, s10
	v_lshl_add_u64 v[74:75], v[6:7], 0, v[74:75]
	global_load_lds_dwordx4 v[76:77], off
	s_mov_b32 m0, s28
	v_mfma_f32_16x16x32_bf16 v[78:81], v[92:95], v[96:99], v[78:81]
	global_load_lds_dwordx4 v[74:75], off
	v_lshl_add_u64 v[74:75], v[16:17], 0, s[4:5]
	s_mov_b32 m0, s36
	v_mfma_f32_16x16x32_bf16 v[88:91], v[104:107], v[96:99], v[88:91]
	global_load_lds_dwordx4 v[74:75], off
	v_lshl_add_u64 v[74:75], v[14:15], 0, s[4:5]
	s_mov_b32 m0, s37
	v_mfma_f32_16x16x32_bf16 v[70:73], v[108:111], v[96:99], v[70:73]
	global_load_lds_dwordx4 v[74:75], off
	v_lshl_add_u64 v[74:75], v[12:13], 0, s[4:5]
	s_mov_b32 m0, s52
	v_mfma_f32_16x16x32_bf16 v[22:25], v[92:95], v[100:103], v[22:25]
	global_load_lds_dwordx4 v[74:75], off
	v_lshl_add_u64 v[74:75], v[10:11], 0, s[4:5]
	s_mov_b32 m0, s53
	v_mfma_f32_16x16x32_bf16 v[42:45], v[104:107], v[100:103], v[42:45]
	global_load_lds_dwordx4 v[74:75], off
	ds_read_b128 v[74:77], v113 offset:49152
	v_mfma_f32_16x16x32_bf16 v[50:53], v[108:111], v[100:103], v[50:53]
	ds_read_b128 v[92:95], v113 offset:51200
	ds_read_b128 v[96:99], v114 offset:32768
	ds_read_b128 v[100:103], v114 offset:34816
	ds_read_b128 v[104:107], v113 offset:53248
	ds_read_b128 v[108:111], v113 offset:55296
	s_waitcnt lgkmcnt(0)
	v_mfma_f32_16x16x32_bf16 v[38:41], v[74:77], v[96:99], v[38:41]
	s_lshl_b32 s4, s54, 6
	s_cmp_lg_u32 s54, 4
	s_cselect_b32 s4, s4, 0
	v_mfma_f32_16x16x32_bf16 v[46:49], v[92:95], v[96:99], v[46:49]
	v_or_b32_e32 v8, s4, v112
	v_lshlrev_b32_e32 v8, 1, v8
	v_lshl_add_u64 v[0:1], v[0:1], 0, v[8:9]
	v_mfma_f32_16x16x32_bf16 v[54:57], v[104:107], v[96:99], v[54:57]
	s_mov_b32 m0, s7
	s_lshl_b32 s28, s4, 1
	s_cmpk_gt_u32 s6, 0x7ff
	v_mfma_f32_16x16x32_bf16 v[30:33], v[108:111], v[96:99], v[30:33]
	v_mfma_f32_16x16x32_bf16 v[58:61], v[74:77], v[100:103], v[58:61]
	v_mfma_f32_16x16x32_bf16 v[62:65], v[92:95], v[100:103], v[62:65]
	v_mfma_f32_16x16x32_bf16 v[66:69], v[104:107], v[100:103], v[66:69]
	v_mfma_f32_16x16x32_bf16 v[34:37], v[108:111], v[100:103], v[34:37]
	ds_read_b128 v[96:99], v114 offset:36864
	ds_read_b128 v[100:103], v114 offset:38912
	s_waitcnt lgkmcnt(1)
	v_mfma_f32_16x16x32_bf16 v[78:81], v[74:77], v[96:99], v[78:81]
	v_mfma_f32_16x16x32_bf16 v[84:87], v[92:95], v[96:99], v[84:87]
	v_mfma_f32_16x16x32_bf16 v[88:91], v[104:107], v[96:99], v[88:91]
	v_mfma_f32_16x16x32_bf16 v[70:73], v[108:111], v[96:99], v[70:73]
	s_waitcnt lgkmcnt(0)
	v_mfma_f32_16x16x32_bf16 v[22:25], v[74:77], v[100:103], v[22:25]
	ds_read_b128 v[74:77], v83 offset:49152
	v_mfma_f32_16x16x32_bf16 v[26:29], v[92:95], v[100:103], v[26:29]
	v_mfma_f32_16x16x32_bf16 v[42:45], v[104:107], v[100:103], v[42:45]
	v_mfma_f32_16x16x32_bf16 v[50:53], v[108:111], v[100:103], v[50:53]
	ds_read_b128 v[92:95], v83 offset:51200
	ds_read_b128 v[96:99], v115 offset:32768
	ds_read_b128 v[100:103], v115 offset:34816
	ds_read_b128 v[104:107], v83 offset:53248
	ds_read_b128 v[108:111], v83 offset:55296
	s_waitcnt lgkmcnt(3)
	v_mfma_f32_16x16x32_bf16 v[38:41], v[74:77], v[96:99], v[38:41]
	v_mfma_f32_16x16x32_bf16 v[46:49], v[92:95], v[96:99], v[46:49]
	s_waitcnt lgkmcnt(1)
	v_mfma_f32_16x16x32_bf16 v[54:57], v[104:107], v[96:99], v[54:57]
	s_waitcnt lgkmcnt(0)
	v_mfma_f32_16x16x32_bf16 v[30:33], v[108:111], v[96:99], v[30:33]
	v_mfma_f32_16x16x32_bf16 v[58:61], v[74:77], v[100:103], v[58:61]
	v_mfma_f32_16x16x32_bf16 v[62:65], v[92:95], v[100:103], v[62:65]
	v_mfma_f32_16x16x32_bf16 v[66:69], v[104:107], v[100:103], v[66:69]
	v_mfma_f32_16x16x32_bf16 v[34:37], v[108:111], v[100:103], v[34:37]
	ds_read_b128 v[96:99], v115 offset:36864
	ds_read_b128 v[100:103], v115 offset:38912
	s_waitcnt vmcnt(0) lgkmcnt(0)
	s_barrier
	global_load_lds_dwordx4 v[0:1], off
	v_lshl_add_u64 v[0:1], v[2:3], 0, v[8:9]
	s_mov_b32 m0, s8
	v_mfma_f32_16x16x32_bf16 v[78:81], v[74:77], v[96:99], v[78:81]
	global_load_lds_dwordx4 v[0:1], off
	v_lshl_add_u64 v[0:1], v[4:5], 0, v[8:9]
	s_mov_b32 m0, s9
	v_mfma_f32_16x16x32_bf16 v[84:87], v[92:95], v[96:99], v[84:87]
	global_load_lds_dwordx4 v[0:1], off
	v_lshl_add_u64 v[0:1], v[6:7], 0, v[8:9]
	s_mov_b32 m0, s11
	v_mfma_f32_16x16x32_bf16 v[22:25], v[74:77], v[100:103], v[22:25]
	global_load_lds_dwordx4 v[0:1], off
	v_lshl_add_u64 v[0:1], v[16:17], 0, s[28:29]
	s_mov_b32 m0, s12
	v_mfma_f32_16x16x32_bf16 v[26:29], v[92:95], v[100:103], v[26:29]
	global_load_lds_dwordx4 v[0:1], off
	v_lshl_add_u64 v[0:1], v[14:15], 0, s[28:29]
	s_mov_b32 m0, s13
	v_mfma_f32_16x16x32_bf16 v[4:7], v[108:111], v[100:103], v[50:53]
	global_load_lds_dwordx4 v[0:1], off
	v_lshl_add_u64 v[0:1], v[12:13], 0, s[28:29]
	s_mov_b32 m0, s34
	v_mfma_f32_16x16x32_bf16 v[88:91], v[104:107], v[96:99], v[88:91]
	global_load_lds_dwordx4 v[0:1], off
	v_lshl_add_u64 v[0:1], v[10:11], 0, s[28:29]
	s_mov_b32 m0, s35
	v_mfma_f32_16x16x32_bf16 v[70:73], v[108:111], v[96:99], v[70:73]
	global_load_lds_dwordx4 v[0:1], off
	ds_read_b128 v[0:3], v113 offset:16384
	ds_read_b128 v[10:13], v113 offset:18432
	ds_read_b128 v[14:17], v114
	ds_read_b128 v[50:53], v114 offset:2048
	ds_read_b128 v[74:77], v113 offset:20480
	ds_read_b128 v[92:95], v113 offset:22528
	s_waitcnt lgkmcnt(0)
	v_mfma_f32_16x16x32_bf16 v[38:41], v[0:3], v[14:17], v[38:41]
	v_and_b32_e32 v8, 48, v18
	v_lshl_or_b32 v8, v20, 8, v8
	v_mad_u64_u32 v[20:21], s[4:5], v19, s31, v[8:9]
	v_mfma_f32_16x16x32_bf16 v[46:49], v[10:13], v[14:17], v[46:49]
	s_cselect_b64 s[34:35], -1, 0
	s_mov_b32 s28, 0
	v_mfma_f32_16x16x32_bf16 v[54:57], v[74:77], v[14:17], v[54:57]
	v_mfma_f32_16x16x32_bf16 v[14:17], v[92:95], v[14:17], v[30:33]
	v_mfma_f32_16x16x32_bf16 v[30:33], v[0:3], v[50:53], v[58:61]
	v_mfma_f32_16x16x32_bf16 v[58:61], v[10:13], v[50:53], v[62:65]
	v_mfma_f32_16x16x32_bf16 v[62:65], v[74:77], v[50:53], v[66:69]
	v_mfma_f32_16x16x32_bf16 v[34:37], v[92:95], v[50:53], v[34:37]
	ds_read_b128 v[50:53], v114 offset:4096
	s_nop 0
	ds_read_b128 v[66:69], v114 offset:6144
	v_mfma_f32_16x16x32_bf16 v[42:45], v[104:107], v[100:103], v[42:45]
	s_waitcnt lgkmcnt(1)
	v_mfma_f32_16x16x32_bf16 v[78:81], v[0:3], v[50:53], v[78:81]
	v_mfma_f32_16x16x32_bf16 v[84:87], v[10:13], v[50:53], v[84:87]
	v_mfma_f32_16x16x32_bf16 v[88:91], v[74:77], v[50:53], v[88:91]
	v_mfma_f32_16x16x32_bf16 v[50:53], v[92:95], v[50:53], v[70:73]
	s_waitcnt lgkmcnt(0)
	v_mfma_f32_16x16x32_bf16 v[0:3], v[0:3], v[66:69], v[22:25]
	v_mfma_f32_16x16x32_bf16 v[10:13], v[10:13], v[66:69], v[26:29]
	v_mfma_f32_16x16x32_bf16 v[22:25], v[74:77], v[66:69], v[42:45]
	s_nop 1
	ds_read_b128 v[26:29], v83 offset:16384
	v_mfma_f32_16x16x32_bf16 v[4:7], v[92:95], v[66:69], v[4:7]
	ds_read_b128 v[42:45], v83 offset:18432
	ds_read_b128 v[66:69], v115
	ds_read_b128 v[70:73], v115 offset:2048
	ds_read_b128 v[74:77], v83 offset:20480
	ds_read_b128 v[92:95], v83 offset:22528
	s_waitcnt lgkmcnt(3)
	v_mfma_f32_16x16x32_bf16 v[38:41], v[26:29], v[66:69], v[38:41]
	v_mfma_f32_16x16x32_bf16 v[46:49], v[42:45], v[66:69], v[46:49]
	s_waitcnt lgkmcnt(1)
	v_mfma_f32_16x16x32_bf16 v[54:57], v[74:77], v[66:69], v[54:57]
	s_waitcnt lgkmcnt(0)
	v_mfma_f32_16x16x32_bf16 v[14:17], v[92:95], v[66:69], v[14:17]
	v_mfma_f32_16x16x32_bf16 v[30:33], v[26:29], v[70:73], v[30:33]
	v_mfma_f32_16x16x32_bf16 v[58:61], v[42:45], v[70:73], v[58:61]
	v_mfma_f32_16x16x32_bf16 v[62:65], v[74:77], v[70:73], v[62:65]
	v_mfma_f32_16x16x32_bf16 v[34:37], v[92:95], v[70:73], v[34:37]
	ds_read_b128 v[66:69], v115 offset:4096
	ds_read_b128 v[70:73], v115 offset:6144
	s_waitcnt vmcnt(0) lgkmcnt(0)
	s_barrier
	v_mfma_f32_16x16x32_bf16 v[78:81], v[26:29], v[66:69], v[78:81]
	v_mfma_f32_16x16x32_bf16 v[84:87], v[42:45], v[66:69], v[84:87]
	v_mfma_f32_16x16x32_bf16 v[88:91], v[74:77], v[66:69], v[88:91]
	v_mfma_f32_16x16x32_bf16 v[50:53], v[92:95], v[66:69], v[50:53]
	ds_read_b128 v[66:69], v113 offset:51200
	v_mfma_f32_16x16x32_bf16 v[0:3], v[26:29], v[70:73], v[0:3]
	ds_read_b128 v[26:29], v113 offset:49152
	v_mfma_f32_16x16x32_bf16 v[10:13], v[42:45], v[70:73], v[10:13]
	ds_read_b128 v[42:45], v114 offset:32768
	v_mfma_f32_16x16x32_bf16 v[22:25], v[74:77], v[70:73], v[22:25]
	ds_read_b128 v[74:77], v113 offset:55296
	v_mfma_f32_16x16x32_bf16 v[4:7], v[92:95], v[70:73], v[4:7]
	ds_read_b128 v[70:73], v113 offset:53248
	s_waitcnt lgkmcnt(2)
	v_mfma_f32_16x16x32_bf16 v[38:41], v[26:29], v[42:45], v[38:41]
	v_mfma_f32_16x16x32_bf16 v[46:49], v[66:69], v[42:45], v[46:49]
	s_waitcnt lgkmcnt(0)
	v_mfma_f32_16x16x32_bf16 v[54:57], v[70:73], v[42:45], v[54:57]
	v_mfma_f32_16x16x32_bf16 v[14:17], v[74:77], v[42:45], v[14:17]
	ds_read_b128 v[42:45], v114 offset:34816
	s_waitcnt lgkmcnt(0)
	v_mfma_f32_16x16x32_bf16 v[30:33], v[26:29], v[42:45], v[30:33]
	v_mfma_f32_16x16x32_bf16 v[58:61], v[66:69], v[42:45], v[58:61]
	v_mfma_f32_16x16x32_bf16 v[62:65], v[70:73], v[42:45], v[62:65]
	v_mfma_f32_16x16x32_bf16 v[34:37], v[74:77], v[42:45], v[34:37]
	ds_read_b128 v[42:45], v114 offset:36864
	s_waitcnt lgkmcnt(0)
	v_mfma_f32_16x16x32_bf16 v[78:81], v[26:29], v[42:45], v[78:81]
	v_mfma_f32_16x16x32_bf16 v[84:87], v[66:69], v[42:45], v[84:87]
	v_mfma_f32_16x16x32_bf16 v[88:91], v[70:73], v[42:45], v[88:91]
	v_mfma_f32_16x16x32_bf16 v[42:45], v[74:77], v[42:45], v[50:53]
	s_nop 2
	ds_read_b128 v[50:53], v114 offset:38912
	s_waitcnt lgkmcnt(0)
	v_mfma_f32_16x16x32_bf16 v[0:3], v[26:29], v[50:53], v[0:3]
	ds_read_b128 v[26:29], v83 offset:49152
	v_mfma_f32_16x16x32_bf16 v[10:13], v[66:69], v[50:53], v[10:13]
	ds_read_b128 v[66:69], v83 offset:51200
	v_mfma_f32_16x16x32_bf16 v[22:25], v[70:73], v[50:53], v[22:25]
	ds_read_b128 v[70:73], v83 offset:53248
	v_mfma_f32_16x16x32_bf16 v[4:7], v[74:77], v[50:53], v[4:7]
	ds_read_b128 v[74:77], v83 offset:55296
	ds_read_b128 v[50:53], v115 offset:32768
	s_waitcnt lgkmcnt(0)
	v_mfma_f32_16x16x32_bf16 v[38:41], v[26:29], v[50:53], v[38:41]
	v_mfma_f32_16x16x32_bf16 v[46:49], v[66:69], v[50:53], v[46:49]
	v_mfma_f32_16x16x32_bf16 v[54:57], v[70:73], v[50:53], v[54:57]
	v_mfma_f32_16x16x32_bf16 v[14:17], v[74:77], v[50:53], v[14:17]
	ds_read_b128 v[50:53], v115 offset:34816
	ds_read_b128 v[92:95], v115 offset:38912
	ds_read_b128 v[96:99], v115 offset:36864
	s_waitcnt lgkmcnt(0)
	v_mfma_f32_16x16x32_bf16 v[30:33], v[26:29], v[50:53], v[30:33]
	s_barrier
	v_mfma_f32_16x16x32_bf16 v[58:61], v[66:69], v[50:53], v[58:61]
	s_barrier
	ds_write_b128 v20, v[38:41]
	ds_write_b128 v20, v[46:49] offset:64
	ds_write_b128 v20, v[54:57] offset:128
	v_mfma_f32_16x16x32_bf16 v[62:65], v[70:73], v[50:53], v[62:65]
	ds_write_b128 v20, v[14:17] offset:192
	ds_write_b128 v20, v[30:33] offset:8448
	s_nop 0
	ds_write_b128 v20, v[58:61] offset:8512
	v_mfma_f32_16x16x32_bf16 v[34:37], v[74:77], v[50:53], v[34:37]
	v_mfma_f32_16x16x32_bf16 v[50:53], v[26:29], v[96:99], v[78:81]
	s_nop 1
	ds_write_b128 v20, v[62:65] offset:8576
	s_nop 3
	ds_write_b128 v20, v[34:37] offset:8640
	ds_write_b128 v20, v[50:53] offset:16896
	v_mfma_f32_16x16x32_bf16 v[78:81], v[66:69], v[96:99], v[84:87]
	v_mfma_f32_16x16x32_bf16 v[0:3], v[26:29], v[92:95], v[0:3]
	v_mfma_f32_16x16x32_bf16 v[84:87], v[70:73], v[96:99], v[88:91]
	v_mfma_f32_16x16x32_bf16 v[10:13], v[66:69], v[92:95], v[10:13]
	v_mfma_f32_16x16x32_bf16 v[38:41], v[74:77], v[96:99], v[42:45]
	s_nop 3
	ds_write_b128 v20, v[78:81] offset:16960
	s_nop 0
	ds_write_b128 v20, v[84:87] offset:17024
	s_nop 0
	ds_write_b128 v20, v[38:41] offset:17088
	v_mfma_f32_16x16x32_bf16 v[14:17], v[70:73], v[92:95], v[22:25]
	ds_write_b128 v20, v[0:3] offset:25344
	ds_write_b128 v20, v[10:13] offset:25408
	s_nop 5
	ds_write_b128 v20, v[14:17] offset:25472
	v_mfma_f32_16x16x32_bf16 v[0:3], v[74:77], v[92:95], v[4:7]
	s_nop 7
	ds_write_b128 v20, v[0:3] offset:25536
	v_lshlrev_b32_e32 v0, 3, v18
	v_and_b32_e32 v1, 0x78, v0
	v_or_b32_e32 v0, s6, v1
	v_lshlrev_b32_e32 v10, 2, v1
	v_ashrrev_i32_e32 v1, 31, v0
	v_mov_b32_e32 v8, v0
	v_cmp_lt_i32_e64 s[4:5], s38, v0
	v_lshl_add_u64 v[12:13], v[0:1], 1, s[80:81]
	v_lshl_add_u64 v[14:15], v[8:9], 2, s[66:67]
	v_lshl_add_u64 v[16:17], v[0:1], 2, s[62:63]
	s_waitcnt lgkmcnt(0)
	s_barrier
	s_branch .LBB0_215

.LBB0_301:
	s_add_i32 s5, s28, 1
	s_cmp_lg_u32 s5, 16
	s_cselect_b32 s28, s5, 0
	s_add_i32 s5, s4, 0x8000
	s_lshl_b32 s30, s28, 6
	s_and_b32 s13, s5, 0x8000
	v_or_b32_e32 v100, s30, v91
	v_add_u32_e32 v102, s13, v92
	v_ashrrev_i32_e32 v101, 31, v100
	v_readfirstlane_b32 s13, v102
	v_add_u32_e32 v104, 0x400, v102
	v_add_u32_e32 v105, 0x800, v102
	v_add_u32_e32 v106, 0xc00, v102
	v_add_u32_e32 v107, 0x4000, v102
	v_add_u32_e32 v108, 0x4400, v102
	v_add_u32_e32 v110, 0x4800, v102
	v_add_u32_e32 v112, 0x4c00, v102
	v_lshlrev_b64 v[102:103], 1, v[100:101]
	v_mov_b32_e32 v101, v65
	s_ashr_i32 s31, s30, 31
	v_lshlrev_b64 v[114:115], 1, v[100:101]
	s_lshl_b64 s[30:31], s[30:31], 1
	v_lshl_add_u64 v[120:121], v[66:67], 0, v[114:115]
	v_readfirstlane_b32 s29, v104
	v_readfirstlane_b32 s34, v105
	v_readfirstlane_b32 s35, v106
	v_lshl_add_u64 v[104:105], v[82:83], 0, s[30:31]
	v_readfirstlane_b32 s36, v107
	v_lshl_add_u64 v[106:107], v[84:85], 0, s[30:31]
	v_readfirstlane_b32 s37, v108
	v_lshl_add_u64 v[108:109], v[86:87], 0, s[30:31]
	v_readfirstlane_b32 s38, v110
	v_lshl_add_u64 v[110:111], v[88:89], 0, s[30:31]
	v_readfirstlane_b32 s30, v112
	v_lshl_add_u64 v[112:113], v[68:69], 0, v[102:103]
	v_lshl_add_u64 v[122:123], v[70:71], 0, v[114:115]
	v_lshl_add_u64 v[120:121], v[120:121], 0, s[10:11]
	v_cmp_gt_i32_e32 vcc, s24, v100
	v_lshl_add_u64 v[116:117], v[72:73], 0, v[102:103]
	v_lshl_add_u64 v[124:125], v[74:75], 0, v[114:115]
	v_lshl_add_u64 v[122:123], v[122:123], 0, s[10:11]
	v_cndmask_b32_e32 v101, v121, v113, vcc
	v_cndmask_b32_e32 v100, v120, v112, vcc
	s_mov_b32 m0, s13
	s_waitcnt vmcnt(0) lgkmcnt(0)
	s_barrier
	v_lshl_add_u64 v[118:119], v[76:77], 0, v[102:103]
	v_lshl_add_u64 v[114:115], v[78:79], 0, v[114:115]
	v_lshl_add_u64 v[124:125], v[124:125], 0, s[10:11]
	v_cndmask_b32_e32 v113, v123, v117, vcc
	v_cndmask_b32_e32 v112, v122, v116, vcc
	global_load_lds_dwordx4 v[100:101], off
	s_mov_b32 m0, s29
	v_lshl_add_u64 v[102:103], v[80:81], 0, v[102:103]
	v_lshl_add_u64 v[114:115], v[114:115], 0, s[10:11]
	v_cndmask_b32_e32 v117, v125, v119, vcc
	v_cndmask_b32_e32 v116, v124, v118, vcc
	global_load_lds_dwordx4 v[112:113], off
	s_mov_b32 m0, s34
	v_cndmask_b32_e32 v103, v115, v103, vcc
	v_cndmask_b32_e32 v102, v114, v102, vcc
	global_load_lds_dwordx4 v[116:117], off
	s_mov_b32 m0, s35
	s_and_b32 s4, s4, 0x8000
	global_load_lds_dwordx4 v[102:103], off
	s_mov_b32 m0, s36
	v_lshl_or_b32 v99, v98, 1, s4
	global_load_lds_dwordx4 v[104:105], off
	s_mov_b32 m0, s37
	v_add_u32_e32 v126, v99, v64
	global_load_lds_dwordx4 v[106:107], off
	s_mov_b32 m0, s38
	v_add_u32_e32 v99, v99, v97
	global_load_lds_dwordx4 v[108:109], off
	s_mov_b32 m0, s30
	s_cmp_eq_u32 s5, 0x78000
	global_load_lds_dwordx4 v[110:111], off
	ds_read_b128 v[100:103], v99 offset:16384
	ds_read_b128 v[104:107], v99 offset:18432
	ds_read_b128 v[108:111], v126
	ds_read_b128 v[112:115], v126 offset:2048
	ds_read_b128 v[116:119], v99 offset:20480
	ds_read_b128 v[120:123], v99 offset:22528
	s_waitcnt lgkmcnt(0)
	v_mfma_f32_16x16x32_bf16 v[60:63], v[100:103], v[108:111], v[60:63]
	v_lshl_or_b32 v99, v96, 1, s4
	v_add_u32_e32 v124, v99, v64
	v_add_u32_e32 v99, v99, v97
	v_mfma_f32_16x16x32_bf16 v[56:59], v[104:107], v[108:111], v[56:59]
	s_mov_b32 s4, s5
	v_mfma_f32_16x16x32_bf16 v[48:51], v[116:119], v[108:111], v[48:51]
	v_mfma_f32_16x16x32_bf16 v[32:35], v[120:123], v[108:111], v[32:35]
	v_mfma_f32_16x16x32_bf16 v[28:31], v[100:103], v[112:115], v[28:31]
	v_mfma_f32_16x16x32_bf16 v[24:27], v[104:107], v[112:115], v[24:27]
	v_mfma_f32_16x16x32_bf16 v[20:23], v[116:119], v[112:115], v[20:23]
	v_mfma_f32_16x16x32_bf16 v[16:19], v[120:123], v[112:115], v[16:19]
	ds_read_b128 v[108:111], v126 offset:4096
	ds_read_b128 v[112:115], v126 offset:6144
	s_waitcnt lgkmcnt(1)
	v_mfma_f32_16x16x32_bf16 v[12:15], v[100:103], v[108:111], v[12:15]
	v_mfma_f32_16x16x32_bf16 v[8:11], v[104:107], v[108:111], v[8:11]
	v_mfma_f32_16x16x32_bf16 v[4:7], v[116:119], v[108:111], v[4:7]
	v_mfma_f32_16x16x32_bf16 v[0:3], v[120:123], v[108:111], v[0:3]
	s_waitcnt lgkmcnt(0)
	v_mfma_f32_16x16x32_bf16 v[44:47], v[100:103], v[112:115], v[44:47]
	v_mfma_f32_16x16x32_bf16 v[52:55], v[104:107], v[112:115], v[52:55]
	ds_read_b128 v[100:103], v99 offset:16384
	ds_read_b128 v[104:107], v99 offset:18432
	v_mfma_f32_16x16x32_bf16 v[40:43], v[116:119], v[112:115], v[40:43]
	v_mfma_f32_16x16x32_bf16 v[36:39], v[120:123], v[112:115], v[36:39]
	ds_read_b128 v[108:111], v124
	ds_read_b128 v[112:115], v124 offset:2048
	ds_read_b128 v[116:119], v99 offset:20480
	ds_read_b128 v[120:123], v99 offset:22528
	s_waitcnt lgkmcnt(3)
	v_mfma_f32_16x16x32_bf16 v[60:63], v[100:103], v[108:111], v[60:63]
	v_mfma_f32_16x16x32_bf16 v[56:59], v[104:107], v[108:111], v[56:59]
	s_waitcnt lgkmcnt(1)
	v_mfma_f32_16x16x32_bf16 v[48:51], v[116:119], v[108:111], v[48:51]
	s_waitcnt lgkmcnt(0)
	v_mfma_f32_16x16x32_bf16 v[32:35], v[120:123], v[108:111], v[32:35]
	v_mfma_f32_16x16x32_bf16 v[28:31], v[100:103], v[112:115], v[28:31]
	v_mfma_f32_16x16x32_bf16 v[24:27], v[104:107], v[112:115], v[24:27]
	v_mfma_f32_16x16x32_bf16 v[20:23], v[116:119], v[112:115], v[20:23]
	v_mfma_f32_16x16x32_bf16 v[16:19], v[120:123], v[112:115], v[16:19]
	ds_read_b128 v[108:111], v124 offset:4096
	ds_read_b128 v[112:115], v124 offset:6144
	s_waitcnt lgkmcnt(1)
	v_mfma_f32_16x16x32_bf16 v[12:15], v[100:103], v[108:111], v[12:15]
	v_mfma_f32_16x16x32_bf16 v[8:11], v[104:107], v[108:111], v[8:11]
	v_mfma_f32_16x16x32_bf16 v[4:7], v[116:119], v[108:111], v[4:7]
	v_mfma_f32_16x16x32_bf16 v[0:3], v[120:123], v[108:111], v[0:3]
	s_waitcnt lgkmcnt(0)
	v_mfma_f32_16x16x32_bf16 v[44:47], v[100:103], v[112:115], v[44:47]
	v_mfma_f32_16x16x32_bf16 v[52:55], v[104:107], v[112:115], v[52:55]
	v_mfma_f32_16x16x32_bf16 v[40:43], v[116:119], v[112:115], v[40:43]
	v_mfma_f32_16x16x32_bf16 v[36:39], v[120:123], v[112:115], v[36:39]
	s_cbranch_scc0 .LBB0_301
	v_lshlrev_b32_e32 v70, 1, v98
	v_add_u32_e32 v82, v70, v97
	v_add_u32_e32 v86, v70, v64
	s_waitcnt vmcnt(0)
	s_barrier
	ds_read_b128 v[66:69], v82 offset:49152
	ds_read_b128 v[74:77], v82 offset:51200
	ds_read_b128 v[70:73], v86 offset:32768
	ds_read_b128 v[78:81], v82 offset:53248
	ds_read_b128 v[82:85], v82 offset:55296
	s_waitcnt lgkmcnt(2)
	v_mfma_f32_16x16x32_bf16 v[60:63], v[66:69], v[70:73], v[60:63]
	v_mfma_f32_16x16x32_bf16 v[56:59], v[74:77], v[70:73], v[56:59]
	s_waitcnt lgkmcnt(1)
	v_mfma_f32_16x16x32_bf16 v[48:51], v[78:81], v[70:73], v[48:51]
	s_waitcnt lgkmcnt(0)
	v_mfma_f32_16x16x32_bf16 v[32:35], v[82:85], v[70:73], v[32:35]
	ds_read_b128 v[70:73], v86 offset:34816
	s_waitcnt lgkmcnt(0)
	v_mfma_f32_16x16x32_bf16 v[28:31], v[66:69], v[70:73], v[28:31]
	v_mfma_f32_16x16x32_bf16 v[24:27], v[74:77], v[70:73], v[24:27]
	v_mfma_f32_16x16x32_bf16 v[20:23], v[78:81], v[70:73], v[20:23]
	v_mfma_f32_16x16x32_bf16 v[16:19], v[82:85], v[70:73], v[16:19]
	ds_read_b128 v[70:73], v86 offset:36864
	s_waitcnt lgkmcnt(0)
	v_mfma_f32_16x16x32_bf16 v[12:15], v[66:69], v[70:73], v[12:15]
	v_mfma_f32_16x16x32_bf16 v[8:11], v[74:77], v[70:73], v[8:11]
	v_mfma_f32_16x16x32_bf16 v[4:7], v[78:81], v[70:73], v[4:7]
	v_mfma_f32_16x16x32_bf16 v[0:3], v[82:85], v[70:73], v[0:3]
	ds_read_b128 v[70:73], v86 offset:38912
	s_waitcnt lgkmcnt(0)
	v_mfma_f32_16x16x32_bf16 v[52:55], v[74:77], v[70:73], v[52:55]
	v_lshlrev_b32_e32 v74, 1, v96
	v_add_u32_e32 v86, v74, v97
	v_add_u32_e32 v64, v74, v64
	v_mfma_f32_16x16x32_bf16 v[44:47], v[66:69], v[70:73], v[44:47]
	ds_read_b128 v[66:69], v86 offset:49152
	ds_read_b128 v[74:77], v86 offset:51200
	v_mfma_f32_16x16x32_bf16 v[40:43], v[78:81], v[70:73], v[40:43]
	ds_read_b128 v[78:81], v86 offset:53248
	v_mfma_f32_16x16x32_bf16 v[36:39], v[82:85], v[70:73], v[36:39]
	ds_read_b128 v[82:85], v86 offset:55296
	ds_read_b128 v[70:73], v64 offset:32768
	s_waitcnt lgkmcnt(0)
	v_mfma_f32_16x16x32_bf16 v[60:63], v[66:69], v[70:73], v[60:63]
	v_mfma_f32_16x16x32_bf16 v[56:59], v[74:77], v[70:73], v[56:59]
	v_mfma_f32_16x16x32_bf16 v[48:51], v[78:81], v[70:73], v[48:51]
	v_mfma_f32_16x16x32_bf16 v[32:35], v[82:85], v[70:73], v[32:35]
	ds_read_b128 v[70:73], v64 offset:34816
	ds_read_b128 v[86:89], v64 offset:38912
	ds_read_b128 v[96:99], v64 offset:36864
	v_and_b32_e32 v64, 48, v90
	s_waitcnt lgkmcnt(2)
	v_mfma_f32_16x16x32_bf16 v[28:31], v[66:69], v[70:73], v[28:31]
	v_lshl_or_b32 v64, v93, 8, v64
	s_waitcnt lgkmcnt(0)
	s_barrier
	v_mfma_f32_16x16x32_bf16 v[20:23], v[78:81], v[70:73], v[20:23]
	s_barrier
	v_mfma_f32_16x16x32_bf16 v[24:27], v[74:77], v[70:73], v[24:27]
	v_mfma_f32_16x16x32_bf16 v[16:19], v[82:85], v[70:73], v[16:19]
	v_lshl_or_b32 v70, v94, 6, v95
	v_mad_u64_u32 v[70:71], s[4:5], v70, s25, v[64:65]
	v_mfma_f32_16x16x32_bf16 v[8:11], v[74:77], v[96:99], v[8:11]
	ds_write_b128 v70, v[60:63]
	ds_write_b128 v70, v[56:59] offset:64
	ds_write_b128 v70, v[48:51] offset:128
	ds_write_b128 v70, v[32:35] offset:192
	ds_write_b128 v70, v[28:31] offset:8448
	ds_write_b128 v70, v[24:27] offset:8512
	v_mfma_f32_16x16x32_bf16 v[12:15], v[66:69], v[96:99], v[12:15]
	ds_write_b128 v70, v[20:23] offset:8576
	ds_write_b128 v70, v[16:19] offset:8640
	s_nop 5
	ds_write_b128 v70, v[12:15] offset:16896
	v_mfma_f32_16x16x32_bf16 v[4:7], v[78:81], v[96:99], v[4:7]
	v_mfma_f32_16x16x32_bf16 v[0:3], v[82:85], v[96:99], v[0:3]
	ds_write_b128 v70, v[8:11] offset:16960
	s_nop 5
	ds_write_b128 v70, v[4:7] offset:17024
	ds_write_b128 v70, v[0:3] offset:17088
	v_and_b32_e32 v4, 64, v139
	v_mfma_f32_16x16x32_bf16 v[24:27], v[66:69], v[86:89], v[44:47]
	v_add_u32_e32 v4, 64, v4
	v_xor_b32_e32 v5, 2, v139
	v_mfma_f32_16x16x32_bf16 v[12:15], v[74:77], v[86:89], v[52:55]
	v_mfma_f32_16x16x32_bf16 v[0:3], v[78:81], v[86:89], v[40:43]
	s_nop 3
	ds_write_b128 v70, v[24:27] offset:25344
	s_nop 1
	ds_write_b128 v70, v[12:15] offset:25408
	ds_write_b128 v70, v[0:3] offset:25472
	v_mfma_f32_16x16x32_bf16 v[0:3], v[82:85], v[86:89], v[36:39]
	s_nop 7
	ds_write_b128 v70, v[0:3] offset:25536
	v_xor_b32_e32 v3, 1, v139
	v_cmp_lt_i32_e32 vcc, v3, v4
	v_lshl_or_b32 v0, v95, 3, s12
	v_ashrrev_i32_e32 v1, 31, v0
	v_cndmask_b32_e32 v3, v139, v3, vcc
	v_cmp_lt_i32_e32 vcc, v5, v4
	v_lshlrev_b32_e32 v2, 5, v95
	s_mov_b32 s12, 0
	v_cndmask_b32_e32 v5, v139, v5, vcc
	v_lshlrev_b32_e32 v10, 2, v5
	v_xor_b32_e32 v5, 4, v139
	v_cmp_lt_i32_e32 vcc, v5, v4
	v_lshlrev_b32_e32 v3, 2, v3
	v_lshl_add_u64 v[6:7], v[0:1], 1, s[58:59]
	v_cndmask_b32_e32 v5, v139, v5, vcc
	v_lshlrev_b32_e32 v11, 2, v5
	v_xor_b32_e32 v5, 8, v139
	v_cmp_lt_i32_e32 vcc, v5, v4
	s_waitcnt lgkmcnt(0)
	s_barrier
	v_cndmask_b32_e32 v4, v139, v5, vcc
	v_lshlrev_b32_e32 v12, 2, v4
	v_cmp_eq_u32_e32 vcc, 0, v95
	v_lshl_add_u64 v[4:5], v[0:1], 2, s[78:79]
	s_branch .LBB0_304

.LBB0_319:
	s_add_i32 s4, s4, 1
	s_cmp_lg_u32 s4, 16
	s_cselect_b32 s4, s4, 0
	s_add_i32 s6, s5, 0x8000
	s_lshl_b32 s8, s4, 6
	s_and_b32 s7, s6, 0x8000
	v_or_b32_e32 v94, s8, v89
	v_add_u32_e32 v96, s7, v88
	s_ashr_i32 s9, s8, 31
	v_ashrrev_i32_e32 v95, 31, v94
	v_readfirstlane_b32 s7, v96
	v_add_u32_e32 v97, 0x400, v96
	v_add_u32_e32 v98, 0x800, v96
	v_add_u32_e32 v99, 0xc00, v96
	v_add_u32_e32 v100, 0x4000, v96
	s_lshl_b64 s[8:9], s[8:9], 1
	v_add_u32_e32 v101, 0x4400, v96
	v_add_u32_e32 v102, 0x4800, v96
	v_add_u32_e32 v104, 0x4c00, v96
	v_lshlrev_b64 v[94:95], 1, v[94:95]
	v_readfirstlane_b32 s16, v97
	v_readfirstlane_b32 s17, v98
	v_readfirstlane_b32 s18, v99
	v_lshl_add_u64 v[96:97], v[74:75], 0, s[8:9]
	v_readfirstlane_b32 s19, v100
	v_lshl_add_u64 v[98:99], v[76:77], 0, s[8:9]
	v_readfirstlane_b32 s22, v101
	v_lshl_add_u64 v[100:101], v[78:79], 0, s[8:9]
	v_readfirstlane_b32 s23, v102
	v_lshl_add_u64 v[102:103], v[80:81], 0, s[8:9]
	v_readfirstlane_b32 s8, v104
	v_lshl_add_u64 v[104:105], v[66:67], 0, v[94:95]
	s_mov_b32 m0, s7
	s_waitcnt vmcnt(0) lgkmcnt(0)
	s_barrier
	v_lshl_add_u64 v[106:107], v[68:69], 0, v[94:95]
	global_load_lds_dwordx4 v[104:105], off
	s_mov_b32 m0, s16
	v_lshl_add_u64 v[108:109], v[70:71], 0, v[94:95]
	global_load_lds_dwordx4 v[106:107], off
	s_mov_b32 m0, s17
	v_lshl_add_u64 v[94:95], v[72:73], 0, v[94:95]
	global_load_lds_dwordx4 v[108:109], off
	s_mov_b32 m0, s18
	s_and_b32 s5, s5, 0x8000
	global_load_lds_dwordx4 v[94:95], off
	s_mov_b32 m0, s19
	v_lshl_or_b32 v93, v92, 1, s5
	global_load_lds_dwordx4 v[96:97], off
	s_mov_b32 m0, s22
	v_add_u32_e32 v118, v93, v64
	global_load_lds_dwordx4 v[98:99], off
	s_mov_b32 m0, s23
	v_add_u32_e32 v93, v93, v91
	global_load_lds_dwordx4 v[100:101], off
	s_mov_b32 m0, s8
	s_cmp_eq_u32 s6, 0x78000
	global_load_lds_dwordx4 v[102:103], off
	ds_read_b128 v[94:97], v93 offset:16384
	ds_read_b128 v[98:101], v93 offset:18432
	ds_read_b128 v[102:105], v118
	ds_read_b128 v[106:109], v118 offset:2048
	ds_read_b128 v[110:113], v93 offset:20480
	ds_read_b128 v[114:117], v93 offset:22528
	s_waitcnt lgkmcnt(0)
	v_mfma_f32_16x16x32_bf16 v[60:63], v[94:97], v[102:105], v[60:63]
	v_lshl_or_b32 v93, v90, 1, s5
	s_mov_b32 s5, s6
	v_mfma_f32_16x16x32_bf16 v[56:59], v[98:101], v[102:105], v[56:59]
	v_mfma_f32_16x16x32_bf16 v[52:55], v[110:113], v[102:105], v[52:55]
	v_mfma_f32_16x16x32_bf16 v[40:43], v[114:117], v[102:105], v[40:43]
	v_mfma_f32_16x16x32_bf16 v[32:35], v[94:97], v[106:109], v[32:35]
	v_mfma_f32_16x16x32_bf16 v[28:31], v[98:101], v[106:109], v[28:31]
	v_mfma_f32_16x16x32_bf16 v[24:27], v[110:113], v[106:109], v[24:27]
	v_mfma_f32_16x16x32_bf16 v[20:23], v[114:117], v[106:109], v[20:23]
	ds_read_b128 v[102:105], v118 offset:4096
	ds_read_b128 v[106:109], v118 offset:6144
	v_add_u32_e32 v118, v93, v64
	v_add_u32_e32 v93, v93, v91
	s_waitcnt lgkmcnt(1)
	v_mfma_f32_16x16x32_bf16 v[12:15], v[94:97], v[102:105], v[12:15]
	v_mfma_f32_16x16x32_bf16 v[8:11], v[98:101], v[102:105], v[8:11]
	v_mfma_f32_16x16x32_bf16 v[4:7], v[110:113], v[102:105], v[4:7]
	v_mfma_f32_16x16x32_bf16 v[0:3], v[114:117], v[102:105], v[0:3]
	s_waitcnt lgkmcnt(0)
	v_mfma_f32_16x16x32_bf16 v[44:47], v[94:97], v[106:109], v[44:47]
	v_mfma_f32_16x16x32_bf16 v[48:51], v[98:101], v[106:109], v[48:51]
	ds_read_b128 v[94:97], v93 offset:16384
	ds_read_b128 v[98:101], v93 offset:18432
	v_mfma_f32_16x16x32_bf16 v[36:39], v[110:113], v[106:109], v[36:39]
	v_mfma_f32_16x16x32_bf16 v[16:19], v[114:117], v[106:109], v[16:19]
	ds_read_b128 v[102:105], v118
	ds_read_b128 v[106:109], v118 offset:2048
	ds_read_b128 v[110:113], v93 offset:20480
	ds_read_b128 v[114:117], v93 offset:22528
	s_waitcnt lgkmcnt(3)
	v_mfma_f32_16x16x32_bf16 v[60:63], v[94:97], v[102:105], v[60:63]
	v_mfma_f32_16x16x32_bf16 v[56:59], v[98:101], v[102:105], v[56:59]
	s_waitcnt lgkmcnt(1)
	v_mfma_f32_16x16x32_bf16 v[52:55], v[110:113], v[102:105], v[52:55]
	s_waitcnt lgkmcnt(0)
	v_mfma_f32_16x16x32_bf16 v[40:43], v[114:117], v[102:105], v[40:43]
	v_mfma_f32_16x16x32_bf16 v[32:35], v[94:97], v[106:109], v[32:35]
	v_mfma_f32_16x16x32_bf16 v[28:31], v[98:101], v[106:109], v[28:31]
	v_mfma_f32_16x16x32_bf16 v[24:27], v[110:113], v[106:109], v[24:27]
	v_mfma_f32_16x16x32_bf16 v[20:23], v[114:117], v[106:109], v[20:23]
	ds_read_b128 v[102:105], v118 offset:4096
	ds_read_b128 v[106:109], v118 offset:6144
	s_waitcnt lgkmcnt(1)
	v_mfma_f32_16x16x32_bf16 v[12:15], v[94:97], v[102:105], v[12:15]
	v_mfma_f32_16x16x32_bf16 v[8:11], v[98:101], v[102:105], v[8:11]
	v_mfma_f32_16x16x32_bf16 v[4:7], v[110:113], v[102:105], v[4:7]
	v_mfma_f32_16x16x32_bf16 v[0:3], v[114:117], v[102:105], v[0:3]
	s_waitcnt lgkmcnt(0)
	v_mfma_f32_16x16x32_bf16 v[44:47], v[94:97], v[106:109], v[44:47]
	v_mfma_f32_16x16x32_bf16 v[48:51], v[98:101], v[106:109], v[48:51]
	v_mfma_f32_16x16x32_bf16 v[36:39], v[110:113], v[106:109], v[36:39]
	v_mfma_f32_16x16x32_bf16 v[16:19], v[114:117], v[106:109], v[16:19]
	s_cbranch_scc0 .LBB0_319
	v_lshlrev_b32_e32 v70, 1, v92
	v_add_u32_e32 v88, v70, v91
	s_waitcnt vmcnt(0)
	s_barrier
	ds_read_b128 v[66:69], v88 offset:49152
	ds_read_b128 v[74:77], v88 offset:51200
	ds_read_b128 v[78:81], v88 offset:53248
	ds_read_b128 v[92:95], v88 offset:55296
	v_add_u32_e32 v89, v70, v64
	ds_read_b128 v[70:73], v89 offset:32768
	s_waitcnt lgkmcnt(0)
	v_mfma_f32_16x16x32_bf16 v[60:63], v[66:69], v[70:73], v[60:63]
	v_lshlrev_b32_e32 v88, 1, v90
	v_add_u32_e32 v104, v88, v91
	v_add_u32_e32 v64, v88, v64
	v_mfma_f32_16x16x32_bf16 v[56:59], v[74:77], v[70:73], v[56:59]
	v_mfma_f32_16x16x32_bf16 v[52:55], v[78:81], v[70:73], v[52:55]
	v_mfma_f32_16x16x32_bf16 v[40:43], v[92:95], v[70:73], v[40:43]
	ds_read_b128 v[70:73], v89 offset:34816
	s_waitcnt lgkmcnt(0)
	v_mfma_f32_16x16x32_bf16 v[32:35], v[66:69], v[70:73], v[32:35]
	v_mfma_f32_16x16x32_bf16 v[28:31], v[74:77], v[70:73], v[28:31]
	v_mfma_f32_16x16x32_bf16 v[24:27], v[78:81], v[70:73], v[24:27]
	v_mfma_f32_16x16x32_bf16 v[20:23], v[92:95], v[70:73], v[20:23]
	ds_read_b128 v[70:73], v89 offset:36864
	s_waitcnt lgkmcnt(0)
	v_mfma_f32_16x16x32_bf16 v[12:15], v[66:69], v[70:73], v[12:15]
	v_mfma_f32_16x16x32_bf16 v[8:11], v[74:77], v[70:73], v[8:11]
	v_mfma_f32_16x16x32_bf16 v[4:7], v[78:81], v[70:73], v[4:7]
	v_mfma_f32_16x16x32_bf16 v[0:3], v[92:95], v[70:73], v[0:3]
	ds_read_b128 v[70:73], v89 offset:38912
	s_waitcnt lgkmcnt(0)
	v_mfma_f32_16x16x32_bf16 v[44:47], v[66:69], v[70:73], v[44:47]
	ds_read_b128 v[66:69], v104 offset:55296
	ds_read_b128 v[88:91], v104 offset:53248
	v_mfma_f32_16x16x32_bf16 v[48:51], v[74:77], v[70:73], v[48:51]
	ds_read_b128 v[74:77], v64 offset:38912
	ds_read_b128 v[96:99], v64 offset:36864
	ds_read_b128 v[100:103], v104 offset:51200
	ds_read_b128 v[104:107], v104 offset:49152
	v_mfma_f32_16x16x32_bf16 v[36:39], v[78:81], v[70:73], v[36:39]
	ds_read_b128 v[78:81], v64 offset:34816
	ds_read_b128 v[108:111], v64 offset:32768
	v_lshlrev_b32_e32 v64, 6, v87
	s_waitcnt lgkmcnt(0)
	v_mfma_f32_16x16x32_bf16 v[16:19], v[92:95], v[70:73], v[16:19]
	v_add_u32_e32 v70, s14, v64
	v_or_b32_e32 v70, v70, v86
	v_ashrrev_i32_e32 v71, 31, v70
	v_lshl_add_u64 v[70:71], v[70:71], 2, s[10:11]
	s_barrier
	global_load_dword v72, v[70:71], off
	global_load_dword v73, v[70:71], off offset:64
	global_load_dword v87, v[70:71], off offset:128
	global_load_dword v92, v[70:71], off offset:192
	v_and_b32_e32 v70, 48, v84
	v_or_b32_e32 v71, v64, v86
	v_lshl_or_b32 v64, v85, 8, v70
	v_mfma_f32_16x16x32_bf16 v[40:43], v[66:69], v[108:111], v[40:43]
	s_barrier
	v_mfma_f32_16x16x32_bf16 v[32:35], v[104:107], v[78:81], v[32:35]
	s_waitcnt vmcnt(3)
	v_fmamk_f32 v70, v72, 0x3a800000, v83
	s_waitcnt vmcnt(2)
	v_fmamk_f32 v72, v73, 0x3a800000, v83
	v_mul_f32_e32 v86, 0x4b800000, v70
	v_cmp_gt_f32_e32 vcc, s12, v70
	s_waitcnt vmcnt(1)
	v_fmamk_f32 v73, v87, 0x3a800000, v83
	v_mul_f32_e32 v87, 0x4b800000, v72
	v_cndmask_b32_e32 v70, v70, v86, vcc
	v_cmp_gt_f32_e64 s[4:5], s12, v72
	v_rsq_f32_e32 v70, v70
	s_waitcnt vmcnt(0)
	v_fmamk_f32 v85, v92, 0x3a800000, v83
	v_cndmask_b32_e64 v72, v72, v87, s[4:5]
	v_mul_f32_e32 v92, 0x4b800000, v73
	v_cmp_gt_f32_e64 s[6:7], s12, v73
	v_rsq_f32_e32 v72, v72
	v_mul_f32_e32 v93, 0x4b800000, v85
	v_cndmask_b32_e64 v73, v73, v92, s[6:7]
	v_cmp_gt_f32_e64 s[8:9], s12, v85
	v_rsq_f32_e32 v73, v73
	v_mfma_f32_16x16x32_bf16 v[28:31], v[100:103], v[78:81], v[28:31]
	v_cndmask_b32_e64 v85, v85, v93, s[8:9]
	v_mul_f32_e32 v86, 0x45800000, v70
	v_rsq_f32_e32 v85, v85
	v_mul_f32_e32 v87, 0x45800000, v72
	v_cndmask_b32_e32 v70, v70, v86, vcc
	v_mfma_f32_16x16x32_bf16 v[24:27], v[88:91], v[78:81], v[24:27]
	v_cndmask_b32_e64 v72, v72, v87, s[4:5]
	v_pk_mul_f32 v[42:43], v[42:43], v[70:71] op_sel_hi:[1,0]
	v_pk_mul_f32 v[40:41], v[40:41], v[70:71] op_sel_hi:[1,0]
	v_mfma_f32_16x16x32_bf16 v[20:23], v[66:69], v[78:81], v[20:23]
	v_mad_u64_u32 v[78:79], s[4:5], v71, s13, v[64:65]
	ds_write_b128 v78, v[40:43] offset:192
	v_mfma_f32_16x16x32_bf16 v[0:3], v[66:69], v[96:99], v[0:3]
	v_mul_f32_e64 v34, v34, v72
	v_mul_f32_e64 v35, v35, v72
	v_pk_mul_f32 v[32:33], v[32:33], v[72:73] op_sel_hi:[1,0]
	v_mul_f32_e32 v92, 0x45800000, v73
	v_mfma_f32_16x16x32_bf16 v[40:43], v[104:107], v[74:77], v[44:47]
	ds_write_b128 v78, v[32:35] offset:8448
	v_pk_mul_f32 v[30:31], v[30:31], v[72:73] op_sel_hi:[1,0]
	v_pk_mul_f32 v[28:29], v[28:29], v[72:73] op_sel_hi:[1,0]
	v_mfma_f32_16x16x32_bf16 v[32:35], v[100:103], v[74:77], v[48:51]
	v_mul_f32_e32 v93, 0x45800000, v85
	v_cndmask_b32_e64 v86, v73, v92, s[6:7]
	ds_write_b128 v78, v[28:31] offset:8512
	v_mfma_f32_16x16x32_bf16 v[28:31], v[88:91], v[74:77], v[36:39]
	v_cndmask_b32_e64 v92, v85, v93, s[8:9]
	v_pk_mul_f32 v[2:3], v[2:3], v[86:87] op_sel_hi:[1,0]
	v_pk_mul_f32 v[0:1], v[0:1], v[86:87] op_sel_hi:[1,0]
	v_mfma_f32_16x16x32_bf16 v[16:19], v[66:69], v[74:77], v[16:19]
	ds_write_b128 v78, v[0:3] offset:17088
	v_pk_mul_f32 v[2:3], v[42:43], v[92:93] op_sel_hi:[1,0]
	v_pk_mul_f32 v[0:1], v[40:41], v[92:93] op_sel_hi:[1,0]
	ds_write_b128 v78, v[0:3] offset:25344
	v_pk_mul_f32 v[2:3], v[34:35], v[92:93] op_sel_hi:[1,0]
	v_pk_mul_f32 v[0:1], v[32:33], v[92:93] op_sel_hi:[1,0]
	ds_write_b128 v78, v[0:3] offset:25408
	v_pk_mul_f32 v[2:3], v[30:31], v[92:93] op_sel_hi:[1,0]
	v_pk_mul_f32 v[0:1], v[28:29], v[92:93] op_sel_hi:[1,0]
	ds_write_b128 v78, v[0:3] offset:25472
	v_pk_mul_f32 v[2:3], v[18:19], v[92:93] op_sel_hi:[1,0]
	v_pk_mul_f32 v[0:1], v[16:17], v[92:93] op_sel_hi:[1,0]
	v_mfma_f32_16x16x32_bf16 v[60:63], v[104:107], v[108:111], v[60:63]
	ds_write_b128 v78, v[0:3] offset:25536
	v_lshlrev_b32_e32 v0, 3, v84
	v_and_b32_e32 v0, 0x78, v0
	v_mfma_f32_16x16x32_bf16 v[56:59], v[100:103], v[108:111], v[56:59]
	v_or_b32_e32 v2, s15, v0
	v_ashrrev_i32_e32 v3, 31, v2
	s_nop 1
	v_pk_mul_f32 v[62:63], v[62:63], v[70:71] op_sel_hi:[1,0]
	v_mfma_f32_16x16x32_bf16 v[52:55], v[88:91], v[108:111], v[52:55]
	v_mul_f32_e64 v60, v60, v70
	v_mul_f32_e64 v61, v61, v70
	v_pk_mul_f32 v[58:59], v[58:59], v[70:71] op_sel_hi:[1,0]
	v_pk_mul_f32 v[56:57], v[56:57], v[70:71] op_sel_hi:[1,0]
	v_mfma_f32_16x16x32_bf16 v[12:15], v[104:107], v[96:99], v[12:15]
	v_mul_f32_e64 v26, v26, v72
	v_mul_f32_e64 v27, v27, v72
	s_nop 0
	v_pk_mul_f32 v[54:55], v[54:55], v[70:71] op_sel_hi:[1,0]
	v_pk_mul_f32 v[52:53], v[52:53], v[70:71] op_sel_hi:[1,0]
	v_mfma_f32_16x16x32_bf16 v[8:11], v[100:103], v[96:99], v[8:11]
	v_mul_f32_e64 v24, v24, v72
	v_mul_f32_e64 v25, v25, v72
	v_pk_mul_f32 v[22:23], v[22:23], v[72:73] op_sel_hi:[1,0]
	v_pk_mul_f32 v[20:21], v[20:21], v[72:73] op_sel_hi:[1,0]
	v_mfma_f32_16x16x32_bf16 v[4:7], v[88:91], v[96:99], v[4:7]
	v_mul_f32_e64 v14, v14, v86
	v_mul_f32_e64 v15, v15, v86
	v_pk_mul_f32 v[12:13], v[12:13], v[86:87] op_sel_hi:[1,0]
	v_pk_mul_f32 v[10:11], v[10:11], v[86:87] op_sel_hi:[1,0]
	v_pk_mul_f32 v[8:9], v[8:9], v[86:87] op_sel_hi:[1,0]
	v_lshlrev_b32_e32 v0, 2, v0
	s_nop 1
	v_pk_mul_f32 v[6:7], v[6:7], v[86:87] op_sel_hi:[1,0]
	v_pk_mul_f32 v[4:5], v[4:5], v[86:87] op_sel_hi:[1,0]
	v_lshl_add_u64 v[2:3], v[2:3], 1, s[80:81]
	s_mov_b32 s4, 0
	ds_write_b128 v78, v[60:63]
	ds_write_b128 v78, v[56:59] offset:64
	ds_write_b128 v78, v[52:55] offset:128
	ds_write_b128 v78, v[24:27] offset:8576
	ds_write_b128 v78, v[20:23] offset:8640
	ds_write_b128 v78, v[12:15] offset:16896
	ds_write_b128 v78, v[8:11] offset:16960
	ds_write_b128 v78, v[4:7] offset:17024
	s_waitcnt lgkmcnt(0)
	s_barrier
